# added hand-written w_out/down bf16 store epilogue with dwordx4 row-contiguous stores (ds_swizzle lane exchange)
# speedup vs baseline: 1.0098x; 1.0062x over previous
.LBB0_1051:
	ds_read_b128 v[152:155], v149
	ds_read_b128 v[156:159], v149 offset:1024
	ds_read_b128 v[160:163], v149 offset:2048
	ds_read_b128 v[164:167], v149 offset:3072
	s_add_u32 s4, s18, 0x100
	s_addc_u32 s5, s19, 0
	s_cmp_eq_u32 s45, 12
	s_cselect_b32 s23, s15, s5
	s_cselect_b32 s22, s14, s4
	s_cselect_b32 s21, s13, s44
	s_cselect_b32 s20, s42, s43
	v_lshl_add_u64 v[168:169], s[18:19], 0, v[140:141]
	s_add_i32 m0, s29, 0xc000
	ds_read_b128 v[172:175], v150
	ds_read_b128 v[176:179], v150 offset:1024
	ds_read_b128 v[180:183], v150 offset:2048
	ds_read_b128 v[184:187], v150 offset:3072
	ds_read_b128 v[188:191], v150 offset:4096
	ds_read_b128 v[192:195], v150 offset:5120
	ds_read_b128 v[196:199], v150 offset:6144
	ds_read_b128 v[200:203], v150 offset:7168
	global_load_lds_dwordx4 v[168:169], off
	v_lshl_add_u64 v[168:169], s[18:19], 0, v[138:139]
	s_add_i32 m0, s29, 0xe000
	s_nop 0
	global_load_lds_dwordx4 v[168:169], off
	s_waitcnt lgkmcnt(8)
	s_barrier
	s_waitcnt lgkmcnt(0)
	s_setprio 1
	s_waitcnt lgkmcnt(0)
	v_mfma_f32_16x16x32_bf16 v[124:127], v[152:155], v[172:175], v[124:127]
	v_mfma_f32_16x16x32_bf16 v[120:123], v[160:163], v[172:175], v[120:123]
	v_mfma_f32_16x16x32_bf16 v[116:119], v[152:155], v[180:183], v[116:119]
	v_mfma_f32_16x16x32_bf16 v[108:111], v[160:163], v[180:183], v[108:111]
	v_mfma_f32_16x16x32_bf16 v[100:103], v[152:155], v[188:191], v[100:103]
	v_mfma_f32_16x16x32_bf16 v[92:95], v[160:163], v[188:191], v[92:95]
	v_mfma_f32_16x16x32_bf16 v[84:87], v[152:155], v[196:199], v[84:87]
	v_mfma_f32_16x16x32_bf16 v[76:79], v[160:163], v[196:199], v[76:79]
	v_mfma_f32_16x16x32_bf16 v[124:127], v[156:159], v[176:179], v[124:127]
	v_mfma_f32_16x16x32_bf16 v[120:123], v[164:167], v[176:179], v[120:123]
	v_mfma_f32_16x16x32_bf16 v[116:119], v[156:159], v[184:187], v[116:119]
	v_mfma_f32_16x16x32_bf16 v[108:111], v[164:167], v[184:187], v[108:111]
	v_mfma_f32_16x16x32_bf16 v[100:103], v[156:159], v[192:195], v[100:103]
	v_mfma_f32_16x16x32_bf16 v[92:95], v[164:167], v[192:195], v[92:95]
	v_mfma_f32_16x16x32_bf16 v[84:87], v[156:159], v[200:203], v[84:87]
	v_mfma_f32_16x16x32_bf16 v[76:79], v[164:167], v[200:203], v[76:79]
	s_setprio 0
	s_barrier
	s_add_i32 s18, s36, s28
	v_lshl_add_u64 v[168:169], s[20:21], 0, v[132:133]
	s_mov_b32 m0, s18
	ds_read_b128 v[204:207], v151
	ds_read_b128 v[208:211], v151 offset:1024
	ds_read_b128 v[212:215], v151 offset:2048
	ds_read_b128 v[216:219], v151 offset:3072
	global_load_lds_dwordx4 v[168:169], off
	v_lshl_add_u64 v[220:221], s[20:21], 0, v[128:129]
	s_add_i32 m0, s18, 0x2000
	s_nop 0
	global_load_lds_dwordx4 v[220:221], off
	s_barrier
	s_waitcnt lgkmcnt(0)
	s_setprio 1
	s_waitcnt lgkmcnt(0)
	v_mfma_f32_16x16x32_bf16 v[112:115], v[204:207], v[172:175], v[112:115]
	v_mfma_f32_16x16x32_bf16 v[104:107], v[212:215], v[172:175], v[104:107]
	v_mfma_f32_16x16x32_bf16 v[96:99], v[204:207], v[180:183], v[96:99]
	v_mfma_f32_16x16x32_bf16 v[88:91], v[212:215], v[180:183], v[88:91]
	v_mfma_f32_16x16x32_bf16 v[80:83], v[204:207], v[188:191], v[80:83]
	v_mfma_f32_16x16x32_bf16 v[72:75], v[212:215], v[188:191], v[72:75]
	v_mfma_f32_16x16x32_bf16 v[68:71], v[204:207], v[196:199], v[68:71]
	v_mfma_f32_16x16x32_bf16 v[64:67], v[212:215], v[196:199], v[64:67]
	v_mfma_f32_16x16x32_bf16 v[112:115], v[208:211], v[176:179], v[112:115]
	v_mfma_f32_16x16x32_bf16 v[104:107], v[216:219], v[176:179], v[104:107]
	v_mfma_f32_16x16x32_bf16 v[96:99], v[208:211], v[184:187], v[96:99]
	v_mfma_f32_16x16x32_bf16 v[88:91], v[216:219], v[184:187], v[88:91]
	v_mfma_f32_16x16x32_bf16 v[80:83], v[208:211], v[192:195], v[80:83]
	v_mfma_f32_16x16x32_bf16 v[72:75], v[216:219], v[192:195], v[72:75]
	v_mfma_f32_16x16x32_bf16 v[68:71], v[208:211], v[200:203], v[68:71]
	v_mfma_f32_16x16x32_bf16 v[64:67], v[216:219], v[200:203], v[64:67]
	s_setprio 0
	s_mov_b32 m0, s29
	v_lshl_add_u64 v[222:223], s[22:23], 0, v[134:135]
	s_barrier
	ds_read_b128 v[172:175], v150 offset:16384
	ds_read_b128 v[176:179], v150 offset:17408
	ds_read_b128 v[180:183], v150 offset:18432
	ds_read_b128 v[184:187], v150 offset:19456
	ds_read_b128 v[188:191], v150 offset:20480
	ds_read_b128 v[192:195], v150 offset:21504
	ds_read_b128 v[196:199], v150 offset:22528
	ds_read_b128 v[200:203], v150 offset:23552
	global_load_lds_dwordx4 v[222:223], off
	v_lshl_add_u64 v[224:225], s[22:23], 0, v[130:131]
	s_mov_b32 m0, s30
	s_nop 0
	global_load_lds_dwordx4 v[224:225], off
	s_barrier
	s_waitcnt lgkmcnt(0)
	s_setprio 1
	s_waitcnt lgkmcnt(0)
	v_mfma_f32_16x16x32_bf16 v[60:63], v[152:155], v[172:175], v[60:63]
	v_mfma_f32_16x16x32_bf16 v[56:59], v[160:163], v[172:175], v[56:59]
	v_mfma_f32_16x16x32_bf16 v[52:55], v[152:155], v[180:183], v[52:55]
	v_mfma_f32_16x16x32_bf16 v[44:47], v[160:163], v[180:183], v[44:47]
	v_mfma_f32_16x16x32_bf16 v[36:39], v[152:155], v[188:191], v[36:39]
	v_mfma_f32_16x16x32_bf16 v[28:31], v[160:163], v[188:191], v[28:31]
	v_mfma_f32_16x16x32_bf16 v[20:23], v[152:155], v[196:199], v[20:23]
	v_mfma_f32_16x16x32_bf16 v[12:15], v[160:163], v[196:199], v[12:15]
	v_mfma_f32_16x16x32_bf16 v[60:63], v[156:159], v[176:179], v[60:63]
	v_mfma_f32_16x16x32_bf16 v[56:59], v[164:167], v[176:179], v[56:59]
	v_mfma_f32_16x16x32_bf16 v[52:55], v[156:159], v[184:187], v[52:55]
	v_mfma_f32_16x16x32_bf16 v[44:47], v[164:167], v[184:187], v[44:47]
	v_mfma_f32_16x16x32_bf16 v[36:39], v[156:159], v[192:195], v[36:39]
	v_mfma_f32_16x16x32_bf16 v[28:31], v[164:167], v[192:195], v[28:31]
	v_mfma_f32_16x16x32_bf16 v[20:23], v[156:159], v[200:203], v[20:23]
	v_mfma_f32_16x16x32_bf16 v[12:15], v[164:167], v[200:203], v[12:15]
	s_setprio 0
	s_barrier
	s_add_u32 s18, s20, 0x40000
	s_addc_u32 s19, s21, 0
	s_add_i32 s46, s37, s28
	v_lshl_add_u64 v[152:153], s[18:19], 0, v[132:133]
	s_mov_b32 m0, s46
	s_nop 0
	global_load_lds_dwordx4 v[152:153], off
	v_lshl_add_u64 v[152:153], s[18:19], 0, v[128:129]
	s_add_i32 m0, s46, 0x2000
	s_nop 0
	global_load_lds_dwordx4 v[152:153], off
	s_waitcnt vmcnt(6)
	s_barrier
	s_setprio 1
	v_mfma_f32_16x16x32_bf16 v[48:51], v[204:207], v[172:175], v[48:51]
	v_mfma_f32_16x16x32_bf16 v[40:43], v[212:215], v[172:175], v[40:43]
	v_mfma_f32_16x16x32_bf16 v[32:35], v[204:207], v[180:183], v[32:35]
	v_mfma_f32_16x16x32_bf16 v[24:27], v[212:215], v[180:183], v[24:27]
	v_mfma_f32_16x16x32_bf16 v[16:19], v[204:207], v[188:191], v[16:19]
	v_mfma_f32_16x16x32_bf16 v[8:11], v[212:215], v[188:191], v[8:11]
	v_mfma_f32_16x16x32_bf16 v[4:7], v[204:207], v[196:199], v[4:7]
	v_mfma_f32_16x16x32_bf16 v[0:3], v[212:215], v[196:199], v[0:3]
	v_mfma_f32_16x16x32_bf16 v[48:51], v[208:211], v[176:179], v[48:51]
	v_mfma_f32_16x16x32_bf16 v[40:43], v[216:219], v[176:179], v[40:43]
	v_mfma_f32_16x16x32_bf16 v[32:35], v[208:211], v[184:187], v[32:35]
	v_mfma_f32_16x16x32_bf16 v[24:27], v[216:219], v[184:187], v[24:27]
	v_mfma_f32_16x16x32_bf16 v[16:19], v[208:211], v[192:195], v[16:19]
	v_mfma_f32_16x16x32_bf16 v[8:11], v[216:219], v[192:195], v[8:11]
	v_mfma_f32_16x16x32_bf16 v[4:7], v[208:211], v[200:203], v[4:7]
	v_mfma_f32_16x16x32_bf16 v[0:3], v[216:219], v[200:203], v[0:3]
	s_setprio 0
	s_add_i32 s46, 0, 0x18000
	v_add_u32_e32 v164, s46, v148
	s_barrier
	ds_read_b128 v[152:155], v164
	ds_read_b128 v[156:159], v164 offset:1024
	ds_read_b128 v[160:163], v164 offset:2048
	ds_read_b128 v[164:167], v164 offset:3072
	s_add_u32 s18, s22, 0xea000
	s_addc_u32 s19, s23, 0
	s_mov_b32 m0, s31
	v_lshl_add_u64 v[204:205], s[18:19], 0, v[134:135]
	ds_read_b128 v[172:175], v150 offset:32768
	ds_read_b128 v[176:179], v150 offset:33792
	ds_read_b128 v[180:183], v150 offset:34816
	ds_read_b128 v[184:187], v150 offset:35840
	ds_read_b128 v[188:191], v150 offset:36864
	ds_read_b128 v[192:195], v150 offset:37888
	ds_read_b128 v[196:199], v150 offset:38912
	ds_read_b128 v[200:203], v150 offset:39936
	global_load_lds_dwordx4 v[204:205], off
	v_lshl_add_u64 v[204:205], s[18:19], 0, v[130:131]
	s_mov_b32 m0, s33
	s_nop 0
	global_load_lds_dwordx4 v[204:205], off
	s_waitcnt lgkmcnt(8)
	s_barrier
	s_waitcnt lgkmcnt(0)
	s_setprio 1
	s_waitcnt lgkmcnt(0)
	v_mfma_f32_16x16x32_bf16 v[124:127], v[152:155], v[172:175], v[124:127]
	v_mfma_f32_16x16x32_bf16 v[120:123], v[160:163], v[172:175], v[120:123]
	v_mfma_f32_16x16x32_bf16 v[116:119], v[152:155], v[180:183], v[116:119]
	v_mfma_f32_16x16x32_bf16 v[108:111], v[160:163], v[180:183], v[108:111]
	v_mfma_f32_16x16x32_bf16 v[100:103], v[152:155], v[188:191], v[100:103]
	v_mfma_f32_16x16x32_bf16 v[92:95], v[160:163], v[188:191], v[92:95]
	v_mfma_f32_16x16x32_bf16 v[84:87], v[152:155], v[196:199], v[84:87]
	v_mfma_f32_16x16x32_bf16 v[76:79], v[160:163], v[196:199], v[76:79]
	v_mfma_f32_16x16x32_bf16 v[124:127], v[156:159], v[176:179], v[124:127]
	v_mfma_f32_16x16x32_bf16 v[120:123], v[164:167], v[176:179], v[120:123]
	v_mfma_f32_16x16x32_bf16 v[116:119], v[156:159], v[184:187], v[116:119]
	v_mfma_f32_16x16x32_bf16 v[108:111], v[164:167], v[184:187], v[108:111]
	v_mfma_f32_16x16x32_bf16 v[100:103], v[156:159], v[192:195], v[100:103]
	v_mfma_f32_16x16x32_bf16 v[92:95], v[164:167], v[192:195], v[92:95]
	v_mfma_f32_16x16x32_bf16 v[84:87], v[156:159], v[200:203], v[84:87]
	v_mfma_f32_16x16x32_bf16 v[76:79], v[164:167], v[200:203], v[76:79]
	s_setprio 0
	s_barrier
	s_add_i32 s22, 0, 0x1c000
	s_add_i32 s18, s46, s28
	v_add_u32_e32 v171, s22, v148
	v_lshl_add_u64 v[168:169], v[168:169], 0, s[10:11]
	s_mov_b32 m0, s18
	ds_read_b128 v[204:207], v171
	ds_read_b128 v[208:211], v171 offset:1024
	ds_read_b128 v[212:215], v171 offset:2048
	ds_read_b128 v[216:219], v171 offset:3072
	global_load_lds_dwordx4 v[168:169], off
	v_lshl_add_u64 v[168:169], v[220:221], 0, s[10:11]
	s_add_i32 m0, s18, 0x2000
	s_nop 0
	global_load_lds_dwordx4 v[168:169], off
	s_barrier
	s_waitcnt lgkmcnt(0)
	s_setprio 1
	s_waitcnt lgkmcnt(0)
	v_mfma_f32_16x16x32_bf16 v[112:115], v[204:207], v[172:175], v[112:115]
	v_mfma_f32_16x16x32_bf16 v[104:107], v[212:215], v[172:175], v[104:107]
	v_mfma_f32_16x16x32_bf16 v[96:99], v[204:207], v[180:183], v[96:99]
	v_mfma_f32_16x16x32_bf16 v[88:91], v[212:215], v[180:183], v[88:91]
	v_mfma_f32_16x16x32_bf16 v[80:83], v[204:207], v[188:191], v[80:83]
	v_mfma_f32_16x16x32_bf16 v[72:75], v[212:215], v[188:191], v[72:75]
	v_mfma_f32_16x16x32_bf16 v[68:71], v[204:207], v[196:199], v[68:71]
	v_mfma_f32_16x16x32_bf16 v[64:67], v[212:215], v[196:199], v[64:67]
	v_mfma_f32_16x16x32_bf16 v[112:115], v[208:211], v[176:179], v[112:115]
	v_mfma_f32_16x16x32_bf16 v[104:107], v[216:219], v[176:179], v[104:107]
	v_mfma_f32_16x16x32_bf16 v[96:99], v[208:211], v[184:187], v[96:99]
	v_mfma_f32_16x16x32_bf16 v[88:91], v[216:219], v[184:187], v[88:91]
	v_mfma_f32_16x16x32_bf16 v[80:83], v[208:211], v[192:195], v[80:83]
	v_mfma_f32_16x16x32_bf16 v[72:75], v[216:219], v[192:195], v[72:75]
	v_mfma_f32_16x16x32_bf16 v[68:71], v[208:211], v[200:203], v[68:71]
	v_mfma_f32_16x16x32_bf16 v[64:67], v[216:219], v[200:203], v[64:67]
	s_setprio 0
	s_mov_b32 m0, s34
	v_lshl_add_u64 v[168:169], v[222:223], 0, s[10:11]
	s_barrier
	ds_read_b128 v[172:175], v150 offset:49152
	ds_read_b128 v[176:179], v150 offset:50176
	ds_read_b128 v[180:183], v150 offset:51200
	ds_read_b128 v[184:187], v150 offset:52224
	ds_read_b128 v[188:191], v150 offset:53248
	ds_read_b128 v[192:195], v150 offset:54272
	ds_read_b128 v[196:199], v150 offset:55296
	ds_read_b128 v[200:203], v150 offset:56320
	global_load_lds_dwordx4 v[168:169], off
	v_lshl_add_u64 v[168:169], v[224:225], 0, s[10:11]
	s_mov_b32 m0, s35
	s_nop 0
	global_load_lds_dwordx4 v[168:169], off
	s_barrier
	s_waitcnt lgkmcnt(0)
	s_setprio 1
	s_waitcnt lgkmcnt(0)
	v_mfma_f32_16x16x32_bf16 v[60:63], v[152:155], v[172:175], v[60:63]
	v_mfma_f32_16x16x32_bf16 v[56:59], v[160:163], v[172:175], v[56:59]
	v_mfma_f32_16x16x32_bf16 v[52:55], v[152:155], v[180:183], v[52:55]
	v_mfma_f32_16x16x32_bf16 v[44:47], v[160:163], v[180:183], v[44:47]
	v_mfma_f32_16x16x32_bf16 v[36:39], v[152:155], v[188:191], v[36:39]
	v_mfma_f32_16x16x32_bf16 v[28:31], v[160:163], v[188:191], v[28:31]
	v_mfma_f32_16x16x32_bf16 v[20:23], v[152:155], v[196:199], v[20:23]
	v_mfma_f32_16x16x32_bf16 v[12:15], v[160:163], v[196:199], v[12:15]
	v_mfma_f32_16x16x32_bf16 v[60:63], v[156:159], v[176:179], v[60:63]
	v_mfma_f32_16x16x32_bf16 v[56:59], v[164:167], v[176:179], v[56:59]
	v_mfma_f32_16x16x32_bf16 v[52:55], v[156:159], v[184:187], v[52:55]
	v_mfma_f32_16x16x32_bf16 v[44:47], v[164:167], v[184:187], v[44:47]
	v_mfma_f32_16x16x32_bf16 v[36:39], v[156:159], v[192:195], v[36:39]
	v_mfma_f32_16x16x32_bf16 v[28:31], v[164:167], v[192:195], v[28:31]
	v_mfma_f32_16x16x32_bf16 v[20:23], v[156:159], v[200:203], v[20:23]
	v_mfma_f32_16x16x32_bf16 v[12:15], v[164:167], v[200:203], v[12:15]
	s_setprio 0
	s_barrier
	s_add_u32 s18, s20, 0x40080
	s_addc_u32 s19, s21, 0
	s_add_i32 s20, s22, s28
	v_lshl_add_u64 v[152:153], s[18:19], 0, v[132:133]
	s_mov_b32 m0, s20
	s_nop 0
	global_load_lds_dwordx4 v[152:153], off
	v_lshl_add_u64 v[152:153], s[18:19], 0, v[128:129]
	s_add_i32 m0, s20, 0x2000
	s_nop 0
	global_load_lds_dwordx4 v[152:153], off
	s_waitcnt vmcnt(6)
	s_barrier
	s_setprio 1
	v_mfma_f32_16x16x32_bf16 v[48:51], v[204:207], v[172:175], v[48:51]
	v_mfma_f32_16x16x32_bf16 v[40:43], v[212:215], v[172:175], v[40:43]
	v_mfma_f32_16x16x32_bf16 v[32:35], v[204:207], v[180:183], v[32:35]
	v_mfma_f32_16x16x32_bf16 v[24:27], v[212:215], v[180:183], v[24:27]
	v_mfma_f32_16x16x32_bf16 v[16:19], v[204:207], v[188:191], v[16:19]
	v_mfma_f32_16x16x32_bf16 v[8:11], v[212:215], v[188:191], v[8:11]
	v_mfma_f32_16x16x32_bf16 v[4:7], v[204:207], v[196:199], v[4:7]
	v_mfma_f32_16x16x32_bf16 v[0:3], v[212:215], v[196:199], v[0:3]
	v_mfma_f32_16x16x32_bf16 v[48:51], v[208:211], v[176:179], v[48:51]
	v_mfma_f32_16x16x32_bf16 v[40:43], v[216:219], v[176:179], v[40:43]
	v_mfma_f32_16x16x32_bf16 v[32:35], v[208:211], v[184:187], v[32:35]
	v_mfma_f32_16x16x32_bf16 v[24:27], v[216:219], v[184:187], v[24:27]
	v_mfma_f32_16x16x32_bf16 v[16:19], v[208:211], v[192:195], v[16:19]
	v_mfma_f32_16x16x32_bf16 v[8:11], v[216:219], v[192:195], v[8:11]
	v_mfma_f32_16x16x32_bf16 v[4:7], v[208:211], v[200:203], v[4:7]
	v_mfma_f32_16x16x32_bf16 v[0:3], v[216:219], v[200:203], v[0:3]
	s_setprio 0
	s_add_i32 s45, s45, 2
	s_add_u32 s43, s43, 0x100
	s_addc_u32 s44, s44, 0
	s_cmp_gt_u32 s45, 13
	s_mov_b64 s[18:19], s[4:5]
	s_barrier
	s_cbranch_scc0 .LBB0_1051
	v_lshl_add_u32 v152, s41, 8, v147
	s_lshl_b32 s4, s40, 8
	v_ashrrev_i32_e32 v153, 31, v152
	s_ashr_i32 s5, s4, 31
	v_lshlrev_b64 v[154:155], 11, v[152:153]
	v_lshl_add_u64 v[154:155], s[6:7], 0, v[154:155]
	s_lshl_b64 s[4:5], s[4:5], 1
	v_lshl_add_u64 v[154:155], v[154:155], 0, s[4:5]
	v_lshl_add_u64 v[154:155], v[154:155], 0, s[8:9]
	v_lshl_add_u64 v[154:155], v[154:155], 0, v[136:137]
	v_mbcnt_lo_u32_b32 v237, -1, 0
	v_mbcnt_hi_u32_b32 v237, -1, v237
	v_bfe_i32 v237, v237, 4, 1
	v_and_b32_e32 v244, 24, v237
	v_add_co_u32_e32 v248, vcc, v244, v154
	s_nop 1
	v_addc_co_u32_e32 v249, vcc, 0, v155, vcc
	v_cvt_pk_bf16_f32 v124, v124, v125
	v_cvt_pk_bf16_f32 v125, v126, v127
	v_cvt_pk_bf16_f32 v120, v120, v121
	v_cvt_pk_bf16_f32 v121, v122, v123
	v_bfi_b32 v244, v237, v124, v120
	v_bfi_b32 v245, v237, v125, v121
	ds_swizzle_b32 v250, v244 offset:0x401f
	ds_swizzle_b32 v251, v245 offset:0x401f
	v_cvt_pk_bf16_f32 v112, v112, v113
	v_cvt_pk_bf16_f32 v113, v114, v115
	v_cvt_pk_bf16_f32 v104, v104, v105
	v_cvt_pk_bf16_f32 v105, v106, v107
	v_bfi_b32 v246, v237, v112, v104
	v_bfi_b32 v247, v237, v113, v105
	ds_swizzle_b32 v252, v246 offset:0x401f
	ds_swizzle_b32 v253, v247 offset:0x401f
	s_waitcnt lgkmcnt(0)
	v_bfi_b32 v240, v237, v250, v124
	v_bfi_b32 v241, v237, v251, v125
	v_bfi_b32 v242, v237, v120, v250
	v_bfi_b32 v243, v237, v121, v251
	global_store_dwordx4 v[248:249], v[240:243], off
	s_nop 1
	v_bfi_b32 v240, v237, v252, v112
	v_bfi_b32 v241, v237, v253, v113
	v_bfi_b32 v242, v237, v104, v252
	v_bfi_b32 v243, v237, v105, v253
	global_store_dwordx4 v[248:249], v[240:243], off offset:256
	s_nop 1
	v_add_co_u32_e32 v238, vcc, 0x8000, v248
	s_nop 1
	v_addc_co_u32_e32 v239, vcc, 0, v249, vcc
	v_cvt_pk_bf16_f32 v116, v116, v117
	v_cvt_pk_bf16_f32 v117, v118, v119
	v_cvt_pk_bf16_f32 v108, v108, v109
	v_cvt_pk_bf16_f32 v109, v110, v111
	v_bfi_b32 v244, v237, v116, v108
	v_bfi_b32 v245, v237, v117, v109
	ds_swizzle_b32 v250, v244 offset:0x401f
	ds_swizzle_b32 v251, v245 offset:0x401f
	v_cvt_pk_bf16_f32 v96, v96, v97
	v_cvt_pk_bf16_f32 v97, v98, v99
	v_cvt_pk_bf16_f32 v88, v88, v89
	v_cvt_pk_bf16_f32 v89, v90, v91
	v_bfi_b32 v246, v237, v96, v88
	v_bfi_b32 v247, v237, v97, v89
	ds_swizzle_b32 v252, v246 offset:0x401f
	ds_swizzle_b32 v253, v247 offset:0x401f
	s_waitcnt lgkmcnt(0)
	v_bfi_b32 v240, v237, v250, v116
	v_bfi_b32 v241, v237, v251, v117
	v_bfi_b32 v242, v237, v108, v250
	v_bfi_b32 v243, v237, v109, v251
	global_store_dwordx4 v[238:239], v[240:243], off
	s_nop 1
	v_bfi_b32 v240, v237, v252, v96
	v_bfi_b32 v241, v237, v253, v97
	v_bfi_b32 v242, v237, v88, v252
	v_bfi_b32 v243, v237, v89, v253
	global_store_dwordx4 v[238:239], v[240:243], off offset:256
	s_nop 1
	v_add_co_u32_e32 v238, vcc, 0x10000, v248
	s_nop 1
	v_addc_co_u32_e32 v239, vcc, 0, v249, vcc
	v_cvt_pk_bf16_f32 v100, v100, v101
	v_cvt_pk_bf16_f32 v101, v102, v103
	v_cvt_pk_bf16_f32 v92, v92, v93
	v_cvt_pk_bf16_f32 v93, v94, v95
	v_bfi_b32 v244, v237, v100, v92
	v_bfi_b32 v245, v237, v101, v93
	ds_swizzle_b32 v250, v244 offset:0x401f
	ds_swizzle_b32 v251, v245 offset:0x401f
	v_cvt_pk_bf16_f32 v80, v80, v81
	v_cvt_pk_bf16_f32 v81, v82, v83
	v_cvt_pk_bf16_f32 v72, v72, v73
	v_cvt_pk_bf16_f32 v73, v74, v75
	v_bfi_b32 v246, v237, v80, v72
	v_bfi_b32 v247, v237, v81, v73
	ds_swizzle_b32 v252, v246 offset:0x401f
	ds_swizzle_b32 v253, v247 offset:0x401f
	s_waitcnt lgkmcnt(0)
	v_bfi_b32 v240, v237, v250, v100
	v_bfi_b32 v241, v237, v251, v101
	v_bfi_b32 v242, v237, v92, v250
	v_bfi_b32 v243, v237, v93, v251
	global_store_dwordx4 v[238:239], v[240:243], off
	s_nop 1
	v_bfi_b32 v240, v237, v252, v80
	v_bfi_b32 v241, v237, v253, v81
	v_bfi_b32 v242, v237, v72, v252
	v_bfi_b32 v243, v237, v73, v253
	global_store_dwordx4 v[238:239], v[240:243], off offset:256
	s_nop 1
	v_add_co_u32_e32 v238, vcc, 0x18000, v248
	s_nop 1
	v_addc_co_u32_e32 v239, vcc, 0, v249, vcc
	v_cvt_pk_bf16_f32 v84, v84, v85
	v_cvt_pk_bf16_f32 v85, v86, v87
	v_cvt_pk_bf16_f32 v76, v76, v77
	v_cvt_pk_bf16_f32 v77, v78, v79
	v_bfi_b32 v244, v237, v84, v76
	v_bfi_b32 v245, v237, v85, v77
	ds_swizzle_b32 v250, v244 offset:0x401f
	ds_swizzle_b32 v251, v245 offset:0x401f
	v_cvt_pk_bf16_f32 v68, v68, v69
	v_cvt_pk_bf16_f32 v69, v70, v71
	v_cvt_pk_bf16_f32 v64, v64, v65
	v_cvt_pk_bf16_f32 v65, v66, v67
	v_bfi_b32 v246, v237, v68, v64
	v_bfi_b32 v247, v237, v69, v65
	ds_swizzle_b32 v252, v246 offset:0x401f
	ds_swizzle_b32 v253, v247 offset:0x401f
	s_waitcnt lgkmcnt(0)
	v_bfi_b32 v240, v237, v250, v84
	v_bfi_b32 v241, v237, v251, v85
	v_bfi_b32 v242, v237, v76, v250
	v_bfi_b32 v243, v237, v77, v251
	global_store_dwordx4 v[238:239], v[240:243], off
	s_nop 1
	v_bfi_b32 v240, v237, v252, v68
	v_bfi_b32 v241, v237, v253, v69
	v_bfi_b32 v242, v237, v64, v252
	v_bfi_b32 v243, v237, v65, v253
	global_store_dwordx4 v[238:239], v[240:243], off offset:256
	s_nop 1
	v_add_co_u32_e32 v238, vcc, 0x40000, v248
	s_nop 1
	v_addc_co_u32_e32 v239, vcc, 0, v249, vcc
	v_cvt_pk_bf16_f32 v60, v60, v61
	v_cvt_pk_bf16_f32 v61, v62, v63
	v_cvt_pk_bf16_f32 v56, v56, v57
	v_cvt_pk_bf16_f32 v57, v58, v59
	v_bfi_b32 v244, v237, v60, v56
	v_bfi_b32 v245, v237, v61, v57
	ds_swizzle_b32 v250, v244 offset:0x401f
	ds_swizzle_b32 v251, v245 offset:0x401f
	v_cvt_pk_bf16_f32 v48, v48, v49
	v_cvt_pk_bf16_f32 v49, v50, v51
	v_cvt_pk_bf16_f32 v40, v40, v41
	v_cvt_pk_bf16_f32 v41, v42, v43
	v_bfi_b32 v246, v237, v48, v40
	v_bfi_b32 v247, v237, v49, v41
	ds_swizzle_b32 v252, v246 offset:0x401f
	ds_swizzle_b32 v253, v247 offset:0x401f
	s_waitcnt lgkmcnt(0)
	v_bfi_b32 v240, v237, v250, v60
	v_bfi_b32 v241, v237, v251, v61
	v_bfi_b32 v242, v237, v56, v250
	v_bfi_b32 v243, v237, v57, v251
	global_store_dwordx4 v[238:239], v[240:243], off
	s_nop 1
	v_bfi_b32 v240, v237, v252, v48
	v_bfi_b32 v241, v237, v253, v49
	v_bfi_b32 v242, v237, v40, v252
	v_bfi_b32 v243, v237, v41, v253
	global_store_dwordx4 v[238:239], v[240:243], off offset:256
	s_nop 1
	v_add_co_u32_e32 v238, vcc, 0x48000, v248
	s_nop 1
	v_addc_co_u32_e32 v239, vcc, 0, v249, vcc
	v_cvt_pk_bf16_f32 v52, v52, v53
	v_cvt_pk_bf16_f32 v53, v54, v55
	v_cvt_pk_bf16_f32 v44, v44, v45
	v_cvt_pk_bf16_f32 v45, v46, v47
	v_bfi_b32 v244, v237, v52, v44
	v_bfi_b32 v245, v237, v53, v45
	ds_swizzle_b32 v250, v244 offset:0x401f
	ds_swizzle_b32 v251, v245 offset:0x401f
	v_cvt_pk_bf16_f32 v32, v32, v33
	v_cvt_pk_bf16_f32 v33, v34, v35
	v_cvt_pk_bf16_f32 v24, v24, v25
	v_cvt_pk_bf16_f32 v25, v26, v27
	v_bfi_b32 v246, v237, v32, v24
	v_bfi_b32 v247, v237, v33, v25
	ds_swizzle_b32 v252, v246 offset:0x401f
	ds_swizzle_b32 v253, v247 offset:0x401f
	s_waitcnt lgkmcnt(0)
	v_bfi_b32 v240, v237, v250, v52
	v_bfi_b32 v241, v237, v251, v53
	v_bfi_b32 v242, v237, v44, v250
	v_bfi_b32 v243, v237, v45, v251
	global_store_dwordx4 v[238:239], v[240:243], off
	s_nop 1
	v_bfi_b32 v240, v237, v252, v32
	v_bfi_b32 v241, v237, v253, v33
	v_bfi_b32 v242, v237, v24, v252
	v_bfi_b32 v243, v237, v25, v253
	global_store_dwordx4 v[238:239], v[240:243], off offset:256
	s_nop 1
	v_add_co_u32_e32 v238, vcc, 0x50000, v248
	s_nop 1
	v_addc_co_u32_e32 v239, vcc, 0, v249, vcc
	v_cvt_pk_bf16_f32 v36, v36, v37
	v_cvt_pk_bf16_f32 v37, v38, v39
	v_cvt_pk_bf16_f32 v28, v28, v29
	v_cvt_pk_bf16_f32 v29, v30, v31
	v_bfi_b32 v244, v237, v36, v28
	v_bfi_b32 v245, v237, v37, v29
	ds_swizzle_b32 v250, v244 offset:0x401f
	ds_swizzle_b32 v251, v245 offset:0x401f
	v_cvt_pk_bf16_f32 v16, v16, v17
	v_cvt_pk_bf16_f32 v17, v18, v19
	v_cvt_pk_bf16_f32 v8, v8, v9
	v_cvt_pk_bf16_f32 v9, v10, v11
	v_bfi_b32 v246, v237, v16, v8
	v_bfi_b32 v247, v237, v17, v9
	ds_swizzle_b32 v252, v246 offset:0x401f
	ds_swizzle_b32 v253, v247 offset:0x401f
	s_waitcnt lgkmcnt(0)
	v_bfi_b32 v240, v237, v250, v36
	v_bfi_b32 v241, v237, v251, v37
	v_bfi_b32 v242, v237, v28, v250
	v_bfi_b32 v243, v237, v29, v251
	global_store_dwordx4 v[238:239], v[240:243], off
	s_nop 1
	v_bfi_b32 v240, v237, v252, v16
	v_bfi_b32 v241, v237, v253, v17
	v_bfi_b32 v242, v237, v8, v252
	v_bfi_b32 v243, v237, v9, v253
	global_store_dwordx4 v[238:239], v[240:243], off offset:256
	s_nop 1
	v_add_co_u32_e32 v238, vcc, 0x58000, v248
	s_nop 1
	v_addc_co_u32_e32 v239, vcc, 0, v249, vcc
	v_cvt_pk_bf16_f32 v20, v20, v21
	v_cvt_pk_bf16_f32 v21, v22, v23
	v_cvt_pk_bf16_f32 v12, v12, v13
	v_cvt_pk_bf16_f32 v13, v14, v15
	v_bfi_b32 v244, v237, v20, v12
	v_bfi_b32 v245, v237, v21, v13
	ds_swizzle_b32 v250, v244 offset:0x401f
	ds_swizzle_b32 v251, v245 offset:0x401f
	v_cvt_pk_bf16_f32 v4, v4, v5
	v_cvt_pk_bf16_f32 v5, v6, v7
	v_cvt_pk_bf16_f32 v0, v0, v1
	v_cvt_pk_bf16_f32 v1, v2, v3
	v_bfi_b32 v246, v237, v4, v0
	v_bfi_b32 v247, v237, v5, v1
	ds_swizzle_b32 v252, v246 offset:0x401f
	ds_swizzle_b32 v253, v247 offset:0x401f
	s_waitcnt lgkmcnt(0)
	v_bfi_b32 v240, v237, v250, v20
	v_bfi_b32 v241, v237, v251, v21
	v_bfi_b32 v242, v237, v12, v250
	v_bfi_b32 v243, v237, v13, v251
	global_store_dwordx4 v[238:239], v[240:243], off
	s_nop 1
	v_bfi_b32 v240, v237, v252, v4
	v_bfi_b32 v241, v237, v253, v5
	v_bfi_b32 v242, v237, v0, v252
	v_bfi_b32 v243, v237, v1, v253
	global_store_dwordx4 v[238:239], v[240:243], off offset:256
	s_nop 1
	s_and_b64 vcc, exec, s[0:1]
	s_mov_b32 s40, s12
	s_mov_b32 s41, s39
	s_mov_b64 s[20:21], s[16:17]
	s_mov_b64 s[18:19], s[14:15]
	s_cbranch_vccz .LBB0_1046
	s_waitcnt vmcnt(0)
	s_cmpk_gt_u32 s3, 0xff
	s_cbranch_scc1 .LBB0_1055
	s_barrier

.LBB0_1284:
	ds_read_b128 v[148:151], v145
	ds_read_b128 v[152:155], v145 offset:1024
	ds_read_b128 v[156:159], v145 offset:2048
	ds_read_b128 v[160:163], v145 offset:3072
	s_add_u32 s14, s12, 0x100
	s_addc_u32 s15, s13, 0
	s_cmp_eq_u32 s44, 40
	s_cselect_b32 s19, s9, s15
	s_cselect_b32 s18, s8, s14
	s_cselect_b32 s17, s1, s43
	s_cselect_b32 s16, s0, s42
	s_mov_b32 m0, s35
	v_lshl_add_u64 v[168:169], s[12:13], 0, v[136:137]
	ds_read_b128 v[164:167], v146
	ds_read_b128 v[172:175], v146 offset:1024
	ds_read_b128 v[176:179], v146 offset:2048
	ds_read_b128 v[180:183], v146 offset:3072
	ds_read_b128 v[184:187], v146 offset:4096
	ds_read_b128 v[188:191], v146 offset:5120
	ds_read_b128 v[192:195], v146 offset:6144
	ds_read_b128 v[196:199], v146 offset:7168
	global_load_lds_dwordx4 v[168:169], off
	v_lshl_add_u64 v[168:169], s[12:13], 0, v[134:135]
	s_mov_b32 m0, s36
	s_nop 0
	global_load_lds_dwordx4 v[168:169], off
	s_waitcnt lgkmcnt(8)
	s_barrier
	s_waitcnt lgkmcnt(0)
	s_setprio 1
	s_waitcnt lgkmcnt(0)
	v_mfma_f32_16x16x32_bf16 v[124:127], v[148:151], v[164:167], v[124:127]
	v_mfma_f32_16x16x32_bf16 v[120:123], v[156:159], v[164:167], v[120:123]
	v_mfma_f32_16x16x32_bf16 v[116:119], v[148:151], v[176:179], v[116:119]
	v_mfma_f32_16x16x32_bf16 v[108:111], v[156:159], v[176:179], v[108:111]
	v_mfma_f32_16x16x32_bf16 v[100:103], v[148:151], v[184:187], v[100:103]
	v_mfma_f32_16x16x32_bf16 v[92:95], v[156:159], v[184:187], v[92:95]
	v_mfma_f32_16x16x32_bf16 v[84:87], v[148:151], v[192:195], v[84:87]
	v_mfma_f32_16x16x32_bf16 v[76:79], v[156:159], v[192:195], v[76:79]
	v_mfma_f32_16x16x32_bf16 v[124:127], v[152:155], v[172:175], v[124:127]
	v_mfma_f32_16x16x32_bf16 v[120:123], v[160:163], v[172:175], v[120:123]
	v_mfma_f32_16x16x32_bf16 v[116:119], v[152:155], v[180:183], v[116:119]
	v_mfma_f32_16x16x32_bf16 v[108:111], v[160:163], v[180:183], v[108:111]
	v_mfma_f32_16x16x32_bf16 v[100:103], v[152:155], v[188:191], v[100:103]
	v_mfma_f32_16x16x32_bf16 v[92:95], v[160:163], v[188:191], v[92:95]
	v_mfma_f32_16x16x32_bf16 v[84:87], v[152:155], v[196:199], v[84:87]
	v_mfma_f32_16x16x32_bf16 v[76:79], v[160:163], v[196:199], v[76:79]
	s_setprio 0
	s_barrier
	s_add_i32 s12, s33, s25
	v_lshl_add_u64 v[168:169], s[16:17], 0, v[130:131]
	s_mov_b32 m0, s12
	ds_read_b128 v[200:203], v147
	ds_read_b128 v[204:207], v147 offset:1024
	ds_read_b128 v[208:211], v147 offset:2048
	ds_read_b128 v[212:215], v147 offset:3072
	global_load_lds_dwordx4 v[168:169], off
	v_lshl_add_u64 v[216:217], s[16:17], 0, v[128:129]
	s_add_i32 m0, s12, 0x2000
	s_nop 0
	global_load_lds_dwordx4 v[216:217], off
	s_barrier
	s_waitcnt lgkmcnt(0)
	s_setprio 1
	s_waitcnt lgkmcnt(0)
	v_mfma_f32_16x16x32_bf16 v[112:115], v[200:203], v[164:167], v[112:115]
	v_mfma_f32_16x16x32_bf16 v[104:107], v[208:211], v[164:167], v[104:107]
	v_mfma_f32_16x16x32_bf16 v[96:99], v[200:203], v[176:179], v[96:99]
	v_mfma_f32_16x16x32_bf16 v[88:91], v[208:211], v[176:179], v[88:91]
	v_mfma_f32_16x16x32_bf16 v[80:83], v[200:203], v[184:187], v[80:83]
	v_mfma_f32_16x16x32_bf16 v[72:75], v[208:211], v[184:187], v[72:75]
	v_mfma_f32_16x16x32_bf16 v[68:71], v[200:203], v[192:195], v[68:71]
	v_mfma_f32_16x16x32_bf16 v[64:67], v[208:211], v[192:195], v[64:67]
	v_mfma_f32_16x16x32_bf16 v[112:115], v[204:207], v[172:175], v[112:115]
	v_mfma_f32_16x16x32_bf16 v[104:107], v[212:215], v[172:175], v[104:107]
	v_mfma_f32_16x16x32_bf16 v[96:99], v[204:207], v[180:183], v[96:99]
	v_mfma_f32_16x16x32_bf16 v[88:91], v[212:215], v[180:183], v[88:91]
	v_mfma_f32_16x16x32_bf16 v[80:83], v[204:207], v[188:191], v[80:83]
	v_mfma_f32_16x16x32_bf16 v[72:75], v[212:215], v[188:191], v[72:75]
	v_mfma_f32_16x16x32_bf16 v[68:71], v[204:207], v[196:199], v[68:71]
	v_mfma_f32_16x16x32_bf16 v[64:67], v[212:215], v[196:199], v[64:67]
	s_setprio 0
	s_mov_b32 m0, s26
	v_lshl_add_u64 v[218:219], s[18:19], 0, v[130:131]
	s_barrier
	ds_read_b128 v[164:167], v146 offset:16384
	ds_read_b128 v[172:175], v146 offset:17408
	ds_read_b128 v[176:179], v146 offset:18432
	ds_read_b128 v[180:183], v146 offset:19456
	ds_read_b128 v[184:187], v146 offset:20480
	ds_read_b128 v[188:191], v146 offset:21504
	ds_read_b128 v[192:195], v146 offset:22528
	ds_read_b128 v[196:199], v146 offset:23552
	global_load_lds_dwordx4 v[218:219], off
	v_lshl_add_u64 v[220:221], s[18:19], 0, v[128:129]
	s_mov_b32 m0, s27
	s_nop 0
	global_load_lds_dwordx4 v[220:221], off
	s_barrier
	s_waitcnt lgkmcnt(0)
	s_setprio 1
	s_waitcnt lgkmcnt(0)
	v_mfma_f32_16x16x32_bf16 v[60:63], v[148:151], v[164:167], v[60:63]
	v_mfma_f32_16x16x32_bf16 v[56:59], v[156:159], v[164:167], v[56:59]
	v_mfma_f32_16x16x32_bf16 v[52:55], v[148:151], v[176:179], v[52:55]
	v_mfma_f32_16x16x32_bf16 v[44:47], v[156:159], v[176:179], v[44:47]
	v_mfma_f32_16x16x32_bf16 v[36:39], v[148:151], v[184:187], v[36:39]
	v_mfma_f32_16x16x32_bf16 v[28:31], v[156:159], v[184:187], v[28:31]
	v_mfma_f32_16x16x32_bf16 v[20:23], v[148:151], v[192:195], v[20:23]
	v_mfma_f32_16x16x32_bf16 v[12:15], v[156:159], v[192:195], v[12:15]
	v_mfma_f32_16x16x32_bf16 v[60:63], v[152:155], v[172:175], v[60:63]
	v_mfma_f32_16x16x32_bf16 v[56:59], v[160:163], v[172:175], v[56:59]
	v_mfma_f32_16x16x32_bf16 v[52:55], v[152:155], v[180:183], v[52:55]
	v_mfma_f32_16x16x32_bf16 v[44:47], v[160:163], v[180:183], v[44:47]
	v_mfma_f32_16x16x32_bf16 v[36:39], v[152:155], v[188:191], v[36:39]
	v_mfma_f32_16x16x32_bf16 v[28:31], v[160:163], v[188:191], v[28:31]
	v_mfma_f32_16x16x32_bf16 v[20:23], v[152:155], v[196:199], v[20:23]
	v_mfma_f32_16x16x32_bf16 v[12:15], v[160:163], v[196:199], v[12:15]
	s_setprio 0
	s_barrier
	s_add_u32 s12, s16, 0xb0000
	s_addc_u32 s13, s17, 0
	s_add_i32 s45, s34, s25
	v_lshl_add_u64 v[148:149], s[12:13], 0, v[130:131]
	s_mov_b32 m0, s45
	s_nop 0
	global_load_lds_dwordx4 v[148:149], off
	v_lshl_add_u64 v[148:149], s[12:13], 0, v[128:129]
	s_add_i32 m0, s45, 0x2000
	s_nop 0
	global_load_lds_dwordx4 v[148:149], off
	s_waitcnt vmcnt(6)
	s_barrier
	s_setprio 1
	v_mfma_f32_16x16x32_bf16 v[48:51], v[200:203], v[164:167], v[48:51]
	v_mfma_f32_16x16x32_bf16 v[40:43], v[208:211], v[164:167], v[40:43]
	v_mfma_f32_16x16x32_bf16 v[32:35], v[200:203], v[176:179], v[32:35]
	v_mfma_f32_16x16x32_bf16 v[24:27], v[208:211], v[176:179], v[24:27]
	v_mfma_f32_16x16x32_bf16 v[16:19], v[200:203], v[184:187], v[16:19]
	v_mfma_f32_16x16x32_bf16 v[8:11], v[208:211], v[184:187], v[8:11]
	v_mfma_f32_16x16x32_bf16 v[4:7], v[200:203], v[192:195], v[4:7]
	v_mfma_f32_16x16x32_bf16 v[0:3], v[208:211], v[192:195], v[0:3]
	v_mfma_f32_16x16x32_bf16 v[48:51], v[204:207], v[172:175], v[48:51]
	v_mfma_f32_16x16x32_bf16 v[40:43], v[212:215], v[172:175], v[40:43]
	v_mfma_f32_16x16x32_bf16 v[32:35], v[204:207], v[180:183], v[32:35]
	v_mfma_f32_16x16x32_bf16 v[24:27], v[212:215], v[180:183], v[24:27]
	v_mfma_f32_16x16x32_bf16 v[16:19], v[204:207], v[188:191], v[16:19]
	v_mfma_f32_16x16x32_bf16 v[8:11], v[212:215], v[188:191], v[8:11]
	v_mfma_f32_16x16x32_bf16 v[4:7], v[204:207], v[196:199], v[4:7]
	v_mfma_f32_16x16x32_bf16 v[0:3], v[212:215], v[196:199], v[0:3]
	s_setprio 0
	s_add_i32 s45, 0, 0x18000
	v_add_u32_e32 v160, s45, v144
	s_barrier
	ds_read_b128 v[148:151], v160
	ds_read_b128 v[152:155], v160 offset:1024
	ds_read_b128 v[156:159], v160 offset:2048
	ds_read_b128 v[160:163], v160 offset:3072
	s_add_u32 s12, s18, 0xb0000
	s_addc_u32 s13, s19, 0
	s_mov_b32 m0, s28
	v_lshl_add_u64 v[200:201], s[12:13], 0, v[130:131]
	ds_read_b128 v[164:167], v146 offset:32768
	ds_read_b128 v[172:175], v146 offset:33792
	ds_read_b128 v[176:179], v146 offset:34816
	ds_read_b128 v[180:183], v146 offset:35840
	ds_read_b128 v[184:187], v146 offset:36864
	ds_read_b128 v[188:191], v146 offset:37888
	ds_read_b128 v[192:195], v146 offset:38912
	ds_read_b128 v[196:199], v146 offset:39936
	global_load_lds_dwordx4 v[200:201], off
	v_lshl_add_u64 v[200:201], s[12:13], 0, v[128:129]
	s_mov_b32 m0, s29
	s_nop 0
	global_load_lds_dwordx4 v[200:201], off
	s_waitcnt lgkmcnt(8)
	s_barrier
	s_waitcnt lgkmcnt(0)
	s_setprio 1
	s_waitcnt lgkmcnt(0)
	v_mfma_f32_16x16x32_bf16 v[124:127], v[148:151], v[164:167], v[124:127]
	v_mfma_f32_16x16x32_bf16 v[120:123], v[156:159], v[164:167], v[120:123]
	v_mfma_f32_16x16x32_bf16 v[116:119], v[148:151], v[176:179], v[116:119]
	v_mfma_f32_16x16x32_bf16 v[108:111], v[156:159], v[176:179], v[108:111]
	v_mfma_f32_16x16x32_bf16 v[100:103], v[148:151], v[184:187], v[100:103]
	v_mfma_f32_16x16x32_bf16 v[92:95], v[156:159], v[184:187], v[92:95]
	v_mfma_f32_16x16x32_bf16 v[84:87], v[148:151], v[192:195], v[84:87]
	v_mfma_f32_16x16x32_bf16 v[76:79], v[156:159], v[192:195], v[76:79]
	v_mfma_f32_16x16x32_bf16 v[124:127], v[152:155], v[172:175], v[124:127]
	v_mfma_f32_16x16x32_bf16 v[120:123], v[160:163], v[172:175], v[120:123]
	v_mfma_f32_16x16x32_bf16 v[116:119], v[152:155], v[180:183], v[116:119]
	v_mfma_f32_16x16x32_bf16 v[108:111], v[160:163], v[180:183], v[108:111]
	v_mfma_f32_16x16x32_bf16 v[100:103], v[152:155], v[188:191], v[100:103]
	v_mfma_f32_16x16x32_bf16 v[92:95], v[160:163], v[188:191], v[92:95]
	v_mfma_f32_16x16x32_bf16 v[84:87], v[152:155], v[196:199], v[84:87]
	v_mfma_f32_16x16x32_bf16 v[76:79], v[160:163], v[196:199], v[76:79]
	s_setprio 0
	s_barrier
	s_add_i32 s18, 0, 0x1c000
	s_add_i32 s12, s45, s25
	v_add_u32_e32 v171, s18, v144
	v_lshl_add_u64 v[168:169], v[168:169], 0, s[10:11]
	s_mov_b32 m0, s12
	ds_read_b128 v[200:203], v171
	ds_read_b128 v[204:207], v171 offset:1024
	ds_read_b128 v[208:211], v171 offset:2048
	ds_read_b128 v[212:215], v171 offset:3072
	global_load_lds_dwordx4 v[168:169], off
	v_lshl_add_u64 v[168:169], v[216:217], 0, s[10:11]
	s_add_i32 m0, s12, 0x2000
	s_nop 0
	global_load_lds_dwordx4 v[168:169], off
	s_barrier
	s_waitcnt lgkmcnt(0)
	s_setprio 1
	s_waitcnt lgkmcnt(0)
	v_mfma_f32_16x16x32_bf16 v[112:115], v[200:203], v[164:167], v[112:115]
	v_mfma_f32_16x16x32_bf16 v[104:107], v[208:211], v[164:167], v[104:107]
	v_mfma_f32_16x16x32_bf16 v[96:99], v[200:203], v[176:179], v[96:99]
	v_mfma_f32_16x16x32_bf16 v[88:91], v[208:211], v[176:179], v[88:91]
	v_mfma_f32_16x16x32_bf16 v[80:83], v[200:203], v[184:187], v[80:83]
	v_mfma_f32_16x16x32_bf16 v[72:75], v[208:211], v[184:187], v[72:75]
	v_mfma_f32_16x16x32_bf16 v[68:71], v[200:203], v[192:195], v[68:71]
	v_mfma_f32_16x16x32_bf16 v[64:67], v[208:211], v[192:195], v[64:67]
	v_mfma_f32_16x16x32_bf16 v[112:115], v[204:207], v[172:175], v[112:115]
	v_mfma_f32_16x16x32_bf16 v[104:107], v[212:215], v[172:175], v[104:107]
	v_mfma_f32_16x16x32_bf16 v[96:99], v[204:207], v[180:183], v[96:99]
	v_mfma_f32_16x16x32_bf16 v[88:91], v[212:215], v[180:183], v[88:91]
	v_mfma_f32_16x16x32_bf16 v[80:83], v[204:207], v[188:191], v[80:83]
	v_mfma_f32_16x16x32_bf16 v[72:75], v[212:215], v[188:191], v[72:75]
	v_mfma_f32_16x16x32_bf16 v[68:71], v[204:207], v[196:199], v[68:71]
	v_mfma_f32_16x16x32_bf16 v[64:67], v[212:215], v[196:199], v[64:67]
	s_setprio 0
	s_mov_b32 m0, s30
	v_lshl_add_u64 v[168:169], v[218:219], 0, s[10:11]
	s_barrier
	ds_read_b128 v[164:167], v146 offset:49152
	ds_read_b128 v[172:175], v146 offset:50176
	ds_read_b128 v[176:179], v146 offset:51200
	ds_read_b128 v[180:183], v146 offset:52224
	ds_read_b128 v[184:187], v146 offset:53248
	ds_read_b128 v[188:191], v146 offset:54272
	ds_read_b128 v[192:195], v146 offset:55296
	ds_read_b128 v[196:199], v146 offset:56320
	global_load_lds_dwordx4 v[168:169], off
	v_lshl_add_u64 v[168:169], v[220:221], 0, s[10:11]
	s_mov_b32 m0, s31
	s_nop 0
	global_load_lds_dwordx4 v[168:169], off
	s_barrier
	s_waitcnt lgkmcnt(0)
	s_setprio 1
	s_waitcnt lgkmcnt(0)
	v_mfma_f32_16x16x32_bf16 v[60:63], v[148:151], v[164:167], v[60:63]
	v_mfma_f32_16x16x32_bf16 v[56:59], v[156:159], v[164:167], v[56:59]
	v_mfma_f32_16x16x32_bf16 v[52:55], v[148:151], v[176:179], v[52:55]
	v_mfma_f32_16x16x32_bf16 v[44:47], v[156:159], v[176:179], v[44:47]
	v_mfma_f32_16x16x32_bf16 v[36:39], v[148:151], v[184:187], v[36:39]
	v_mfma_f32_16x16x32_bf16 v[28:31], v[156:159], v[184:187], v[28:31]
	v_mfma_f32_16x16x32_bf16 v[20:23], v[148:151], v[192:195], v[20:23]
	v_mfma_f32_16x16x32_bf16 v[12:15], v[156:159], v[192:195], v[12:15]
	v_mfma_f32_16x16x32_bf16 v[60:63], v[152:155], v[172:175], v[60:63]
	v_mfma_f32_16x16x32_bf16 v[56:59], v[160:163], v[172:175], v[56:59]
	v_mfma_f32_16x16x32_bf16 v[52:55], v[152:155], v[180:183], v[52:55]
	v_mfma_f32_16x16x32_bf16 v[44:47], v[160:163], v[180:183], v[44:47]
	v_mfma_f32_16x16x32_bf16 v[36:39], v[152:155], v[188:191], v[36:39]
	v_mfma_f32_16x16x32_bf16 v[28:31], v[160:163], v[188:191], v[28:31]
	v_mfma_f32_16x16x32_bf16 v[20:23], v[152:155], v[196:199], v[20:23]
	v_mfma_f32_16x16x32_bf16 v[12:15], v[160:163], v[196:199], v[12:15]
	s_setprio 0
	s_barrier
	s_add_u32 s12, s16, 0xb0080
	s_addc_u32 s13, s17, 0
	s_add_i32 s16, s18, s25
	v_lshl_add_u64 v[148:149], s[12:13], 0, v[130:131]
	s_mov_b32 m0, s16
	s_nop 0
	global_load_lds_dwordx4 v[148:149], off
	v_lshl_add_u64 v[148:149], s[12:13], 0, v[128:129]
	s_add_i32 m0, s16, 0x2000
	s_nop 0
	global_load_lds_dwordx4 v[148:149], off
	s_waitcnt vmcnt(6)
	s_barrier
	s_setprio 1
	v_mfma_f32_16x16x32_bf16 v[48:51], v[200:203], v[164:167], v[48:51]
	v_mfma_f32_16x16x32_bf16 v[40:43], v[208:211], v[164:167], v[40:43]
	v_mfma_f32_16x16x32_bf16 v[32:35], v[200:203], v[176:179], v[32:35]
	v_mfma_f32_16x16x32_bf16 v[24:27], v[208:211], v[176:179], v[24:27]
	v_mfma_f32_16x16x32_bf16 v[16:19], v[200:203], v[184:187], v[16:19]
	v_mfma_f32_16x16x32_bf16 v[8:11], v[208:211], v[184:187], v[8:11]
	v_mfma_f32_16x16x32_bf16 v[4:7], v[200:203], v[192:195], v[4:7]
	v_mfma_f32_16x16x32_bf16 v[0:3], v[208:211], v[192:195], v[0:3]
	v_mfma_f32_16x16x32_bf16 v[48:51], v[204:207], v[172:175], v[48:51]
	v_mfma_f32_16x16x32_bf16 v[40:43], v[212:215], v[172:175], v[40:43]
	v_mfma_f32_16x16x32_bf16 v[32:35], v[204:207], v[180:183], v[32:35]
	v_mfma_f32_16x16x32_bf16 v[24:27], v[212:215], v[180:183], v[24:27]
	v_mfma_f32_16x16x32_bf16 v[16:19], v[204:207], v[188:191], v[16:19]
	v_mfma_f32_16x16x32_bf16 v[8:11], v[212:215], v[188:191], v[8:11]
	v_mfma_f32_16x16x32_bf16 v[4:7], v[204:207], v[196:199], v[4:7]
	v_mfma_f32_16x16x32_bf16 v[0:3], v[212:215], v[196:199], v[0:3]
	s_setprio 0
	s_add_i32 s44, s44, 2
	s_add_u32 s42, s42, 0x100
	s_addc_u32 s43, s43, 0
	s_cmp_gt_u32 s44, 41
	s_mov_b64 s[12:13], s[14:15]
	s_barrier
	s_cbranch_scc0 .LBB0_1284
	v_lshl_add_u32 v148, s41, 8, v143
	s_lshl_b32 s12, s40, 8
	v_ashrrev_i32_e32 v149, 31, v148
	s_ashr_i32 s13, s12, 31
	v_lshlrev_b64 v[150:151], 11, v[148:149]
	v_lshl_add_u64 v[150:151], s[4:5], 0, v[150:151]
	s_lshl_b64 s[12:13], s[12:13], 1
	v_lshl_add_u64 v[150:151], v[150:151], 0, s[12:13]
	v_lshl_add_u64 v[150:151], v[150:151], 0, s[2:3]
	v_lshl_add_u64 v[150:151], v[150:151], 0, v[132:133]
	v_mbcnt_lo_u32_b32 v237, -1, 0
	v_mbcnt_hi_u32_b32 v237, -1, v237
	v_bfe_i32 v237, v237, 4, 1
	v_and_b32_e32 v244, 24, v237
	v_add_co_u32_e32 v248, vcc, v244, v150
	s_nop 1
	v_addc_co_u32_e32 v249, vcc, 0, v151, vcc
	v_cvt_pk_bf16_f32 v124, v124, v125
	v_cvt_pk_bf16_f32 v125, v126, v127
	v_cvt_pk_bf16_f32 v120, v120, v121
	v_cvt_pk_bf16_f32 v121, v122, v123
	v_bfi_b32 v244, v237, v124, v120
	v_bfi_b32 v245, v237, v125, v121
	ds_swizzle_b32 v250, v244 offset:0x401f
	ds_swizzle_b32 v251, v245 offset:0x401f
	v_cvt_pk_bf16_f32 v112, v112, v113
	v_cvt_pk_bf16_f32 v113, v114, v115
	v_cvt_pk_bf16_f32 v104, v104, v105
	v_cvt_pk_bf16_f32 v105, v106, v107
	v_bfi_b32 v246, v237, v112, v104
	v_bfi_b32 v247, v237, v113, v105
	ds_swizzle_b32 v252, v246 offset:0x401f
	ds_swizzle_b32 v253, v247 offset:0x401f
	s_waitcnt lgkmcnt(0)
	v_bfi_b32 v240, v237, v250, v124
	v_bfi_b32 v241, v237, v251, v125
	v_bfi_b32 v242, v237, v120, v250
	v_bfi_b32 v243, v237, v121, v251
	global_store_dwordx4 v[248:249], v[240:243], off
	s_nop 1
	v_bfi_b32 v240, v237, v252, v112
	v_bfi_b32 v241, v237, v253, v113
	v_bfi_b32 v242, v237, v104, v252
	v_bfi_b32 v243, v237, v105, v253
	global_store_dwordx4 v[248:249], v[240:243], off offset:256
	s_nop 1
	v_add_co_u32_e32 v238, vcc, 0x8000, v248
	s_nop 1
	v_addc_co_u32_e32 v239, vcc, 0, v249, vcc
	v_cvt_pk_bf16_f32 v116, v116, v117
	v_cvt_pk_bf16_f32 v117, v118, v119
	v_cvt_pk_bf16_f32 v108, v108, v109
	v_cvt_pk_bf16_f32 v109, v110, v111
	v_bfi_b32 v244, v237, v116, v108
	v_bfi_b32 v245, v237, v117, v109
	ds_swizzle_b32 v250, v244 offset:0x401f
	ds_swizzle_b32 v251, v245 offset:0x401f
	v_cvt_pk_bf16_f32 v96, v96, v97
	v_cvt_pk_bf16_f32 v97, v98, v99
	v_cvt_pk_bf16_f32 v88, v88, v89
	v_cvt_pk_bf16_f32 v89, v90, v91
	v_bfi_b32 v246, v237, v96, v88
	v_bfi_b32 v247, v237, v97, v89
	ds_swizzle_b32 v252, v246 offset:0x401f
	ds_swizzle_b32 v253, v247 offset:0x401f
	s_waitcnt lgkmcnt(0)
	v_bfi_b32 v240, v237, v250, v116
	v_bfi_b32 v241, v237, v251, v117
	v_bfi_b32 v242, v237, v108, v250
	v_bfi_b32 v243, v237, v109, v251
	global_store_dwordx4 v[238:239], v[240:243], off
	s_nop 1
	v_bfi_b32 v240, v237, v252, v96
	v_bfi_b32 v241, v237, v253, v97
	v_bfi_b32 v242, v237, v88, v252
	v_bfi_b32 v243, v237, v89, v253
	global_store_dwordx4 v[238:239], v[240:243], off offset:256
	s_nop 1
	v_add_co_u32_e32 v238, vcc, 0x10000, v248
	s_nop 1
	v_addc_co_u32_e32 v239, vcc, 0, v249, vcc
	v_cvt_pk_bf16_f32 v100, v100, v101
	v_cvt_pk_bf16_f32 v101, v102, v103
	v_cvt_pk_bf16_f32 v92, v92, v93
	v_cvt_pk_bf16_f32 v93, v94, v95
	v_bfi_b32 v244, v237, v100, v92
	v_bfi_b32 v245, v237, v101, v93
	ds_swizzle_b32 v250, v244 offset:0x401f
	ds_swizzle_b32 v251, v245 offset:0x401f
	v_cvt_pk_bf16_f32 v80, v80, v81
	v_cvt_pk_bf16_f32 v81, v82, v83
	v_cvt_pk_bf16_f32 v72, v72, v73
	v_cvt_pk_bf16_f32 v73, v74, v75
	v_bfi_b32 v246, v237, v80, v72
	v_bfi_b32 v247, v237, v81, v73
	ds_swizzle_b32 v252, v246 offset:0x401f
	ds_swizzle_b32 v253, v247 offset:0x401f
	s_waitcnt lgkmcnt(0)
	v_bfi_b32 v240, v237, v250, v100
	v_bfi_b32 v241, v237, v251, v101
	v_bfi_b32 v242, v237, v92, v250
	v_bfi_b32 v243, v237, v93, v251
	global_store_dwordx4 v[238:239], v[240:243], off
	s_nop 1
	v_bfi_b32 v240, v237, v252, v80
	v_bfi_b32 v241, v237, v253, v81
	v_bfi_b32 v242, v237, v72, v252
	v_bfi_b32 v243, v237, v73, v253
	global_store_dwordx4 v[238:239], v[240:243], off offset:256
	s_nop 1
	v_add_co_u32_e32 v238, vcc, 0x18000, v248
	s_nop 1
	v_addc_co_u32_e32 v239, vcc, 0, v249, vcc
	v_cvt_pk_bf16_f32 v84, v84, v85
	v_cvt_pk_bf16_f32 v85, v86, v87
	v_cvt_pk_bf16_f32 v76, v76, v77
	v_cvt_pk_bf16_f32 v77, v78, v79
	v_bfi_b32 v244, v237, v84, v76
	v_bfi_b32 v245, v237, v85, v77
	ds_swizzle_b32 v250, v244 offset:0x401f
	ds_swizzle_b32 v251, v245 offset:0x401f
	v_cvt_pk_bf16_f32 v68, v68, v69
	v_cvt_pk_bf16_f32 v69, v70, v71
	v_cvt_pk_bf16_f32 v64, v64, v65
	v_cvt_pk_bf16_f32 v65, v66, v67
	v_bfi_b32 v246, v237, v68, v64
	v_bfi_b32 v247, v237, v69, v65
	ds_swizzle_b32 v252, v246 offset:0x401f
	ds_swizzle_b32 v253, v247 offset:0x401f
	s_waitcnt lgkmcnt(0)
	v_bfi_b32 v240, v237, v250, v84
	v_bfi_b32 v241, v237, v251, v85
	v_bfi_b32 v242, v237, v76, v250
	v_bfi_b32 v243, v237, v77, v251
	global_store_dwordx4 v[238:239], v[240:243], off
	s_nop 1
	v_bfi_b32 v240, v237, v252, v68
	v_bfi_b32 v241, v237, v253, v69
	v_bfi_b32 v242, v237, v64, v252
	v_bfi_b32 v243, v237, v65, v253
	global_store_dwordx4 v[238:239], v[240:243], off offset:256
	s_nop 1
	v_add_co_u32_e32 v238, vcc, 0x40000, v248
	s_nop 1
	v_addc_co_u32_e32 v239, vcc, 0, v249, vcc
	v_cvt_pk_bf16_f32 v60, v60, v61
	v_cvt_pk_bf16_f32 v61, v62, v63
	v_cvt_pk_bf16_f32 v56, v56, v57
	v_cvt_pk_bf16_f32 v57, v58, v59
	v_bfi_b32 v244, v237, v60, v56
	v_bfi_b32 v245, v237, v61, v57
	ds_swizzle_b32 v250, v244 offset:0x401f
	ds_swizzle_b32 v251, v245 offset:0x401f
	v_cvt_pk_bf16_f32 v48, v48, v49
	v_cvt_pk_bf16_f32 v49, v50, v51
	v_cvt_pk_bf16_f32 v40, v40, v41
	v_cvt_pk_bf16_f32 v41, v42, v43
	v_bfi_b32 v246, v237, v48, v40
	v_bfi_b32 v247, v237, v49, v41
	ds_swizzle_b32 v252, v246 offset:0x401f
	ds_swizzle_b32 v253, v247 offset:0x401f
	s_waitcnt lgkmcnt(0)
	v_bfi_b32 v240, v237, v250, v60
	v_bfi_b32 v241, v237, v251, v61
	v_bfi_b32 v242, v237, v56, v250
	v_bfi_b32 v243, v237, v57, v251
	global_store_dwordx4 v[238:239], v[240:243], off
	s_nop 1
	v_bfi_b32 v240, v237, v252, v48
	v_bfi_b32 v241, v237, v253, v49
	v_bfi_b32 v242, v237, v40, v252
	v_bfi_b32 v243, v237, v41, v253
	global_store_dwordx4 v[238:239], v[240:243], off offset:256
	s_nop 1
	v_add_co_u32_e32 v238, vcc, 0x48000, v248
	s_nop 1
	v_addc_co_u32_e32 v239, vcc, 0, v249, vcc
	v_cvt_pk_bf16_f32 v52, v52, v53
	v_cvt_pk_bf16_f32 v53, v54, v55
	v_cvt_pk_bf16_f32 v44, v44, v45
	v_cvt_pk_bf16_f32 v45, v46, v47
	v_bfi_b32 v244, v237, v52, v44
	v_bfi_b32 v245, v237, v53, v45
	ds_swizzle_b32 v250, v244 offset:0x401f
	ds_swizzle_b32 v251, v245 offset:0x401f
	v_cvt_pk_bf16_f32 v32, v32, v33
	v_cvt_pk_bf16_f32 v33, v34, v35
	v_cvt_pk_bf16_f32 v24, v24, v25
	v_cvt_pk_bf16_f32 v25, v26, v27
	v_bfi_b32 v246, v237, v32, v24
	v_bfi_b32 v247, v237, v33, v25
	ds_swizzle_b32 v252, v246 offset:0x401f
	ds_swizzle_b32 v253, v247 offset:0x401f
	s_waitcnt lgkmcnt(0)
	v_bfi_b32 v240, v237, v250, v52
	v_bfi_b32 v241, v237, v251, v53
	v_bfi_b32 v242, v237, v44, v250
	v_bfi_b32 v243, v237, v45, v251
	global_store_dwordx4 v[238:239], v[240:243], off
	s_nop 1
	v_bfi_b32 v240, v237, v252, v32
	v_bfi_b32 v241, v237, v253, v33
	v_bfi_b32 v242, v237, v24, v252
	v_bfi_b32 v243, v237, v25, v253
	global_store_dwordx4 v[238:239], v[240:243], off offset:256
	s_nop 1
	v_add_co_u32_e32 v238, vcc, 0x50000, v248
	s_nop 1
	v_addc_co_u32_e32 v239, vcc, 0, v249, vcc
	v_cvt_pk_bf16_f32 v36, v36, v37
	v_cvt_pk_bf16_f32 v37, v38, v39
	v_cvt_pk_bf16_f32 v28, v28, v29
	v_cvt_pk_bf16_f32 v29, v30, v31
	v_bfi_b32 v244, v237, v36, v28
	v_bfi_b32 v245, v237, v37, v29
	ds_swizzle_b32 v250, v244 offset:0x401f
	ds_swizzle_b32 v251, v245 offset:0x401f
	v_cvt_pk_bf16_f32 v16, v16, v17
	v_cvt_pk_bf16_f32 v17, v18, v19
	v_cvt_pk_bf16_f32 v8, v8, v9
	v_cvt_pk_bf16_f32 v9, v10, v11
	v_bfi_b32 v246, v237, v16, v8
	v_bfi_b32 v247, v237, v17, v9
	ds_swizzle_b32 v252, v246 offset:0x401f
	ds_swizzle_b32 v253, v247 offset:0x401f
	s_waitcnt lgkmcnt(0)
	v_bfi_b32 v240, v237, v250, v36
	v_bfi_b32 v241, v237, v251, v37
	v_bfi_b32 v242, v237, v28, v250
	v_bfi_b32 v243, v237, v29, v251
	global_store_dwordx4 v[238:239], v[240:243], off
	s_nop 1
	v_bfi_b32 v240, v237, v252, v16
	v_bfi_b32 v241, v237, v253, v17
	v_bfi_b32 v242, v237, v8, v252
	v_bfi_b32 v243, v237, v9, v253
	global_store_dwordx4 v[238:239], v[240:243], off offset:256
	s_nop 1
	v_add_co_u32_e32 v238, vcc, 0x58000, v248
	s_nop 1
	v_addc_co_u32_e32 v239, vcc, 0, v249, vcc
	v_cvt_pk_bf16_f32 v20, v20, v21
	v_cvt_pk_bf16_f32 v21, v22, v23
	v_cvt_pk_bf16_f32 v12, v12, v13
	v_cvt_pk_bf16_f32 v13, v14, v15
	v_bfi_b32 v244, v237, v20, v12
	v_bfi_b32 v245, v237, v21, v13
	ds_swizzle_b32 v250, v244 offset:0x401f
	ds_swizzle_b32 v251, v245 offset:0x401f
	v_cvt_pk_bf16_f32 v4, v4, v5
	v_cvt_pk_bf16_f32 v5, v6, v7
	v_cvt_pk_bf16_f32 v0, v0, v1
	v_cvt_pk_bf16_f32 v1, v2, v3
	v_bfi_b32 v246, v237, v4, v0
	v_bfi_b32 v247, v237, v5, v1
	ds_swizzle_b32 v252, v246 offset:0x401f
	ds_swizzle_b32 v253, v247 offset:0x401f
	s_waitcnt lgkmcnt(0)
	v_bfi_b32 v240, v237, v250, v20
	v_bfi_b32 v241, v237, v251, v21
	v_bfi_b32 v242, v237, v12, v250
	v_bfi_b32 v243, v237, v13, v251
	global_store_dwordx4 v[238:239], v[240:243], off
	s_nop 1
	v_bfi_b32 v240, v237, v252, v4
	v_bfi_b32 v241, v237, v253, v5
	v_bfi_b32 v242, v237, v0, v252
	v_bfi_b32 v243, v237, v1, v253
	global_store_dwordx4 v[238:239], v[240:243], off offset:256
	s_nop 1
	s_and_b64 vcc, exec, s[6:7]
	s_mov_b32 s40, s38
	s_mov_b32 s41, s39
	s_mov_b64 s[14:15], s[0:1]
	s_mov_b64 s[12:13], s[8:9]
	s_cbranch_vccz .LBB0_1277
	s_waitcnt vmcnt(0)
	s_cmpk_gt_u32 s20, 0xff
	s_cbranch_scc1 .LBB0_1288
	s_barrier

.LBB0_2046:
	ds_read_b128 v[152:155], v149
	ds_read_b128 v[156:159], v149 offset:1024
	ds_read_b128 v[160:163], v149 offset:2048
	ds_read_b128 v[164:167], v149 offset:3072
	s_add_u32 s8, s16, 0x100
	s_addc_u32 s9, s17, 0
	s_cmp_eq_u32 s45, 12
	s_cselect_b32 s21, s13, s9
	s_cselect_b32 s20, s12, s8
	s_cselect_b32 s19, s11, s44
	s_cselect_b32 s18, s42, s43
	v_lshl_add_u64 v[168:169], s[16:17], 0, v[140:141]
	s_add_i32 m0, s28, 0xc000
	ds_read_b128 v[172:175], v150
	ds_read_b128 v[176:179], v150 offset:1024
	ds_read_b128 v[180:183], v150 offset:2048
	ds_read_b128 v[184:187], v150 offset:3072
	ds_read_b128 v[188:191], v150 offset:4096
	ds_read_b128 v[192:195], v150 offset:5120
	ds_read_b128 v[196:199], v150 offset:6144
	ds_read_b128 v[200:203], v150 offset:7168
	global_load_lds_dwordx4 v[168:169], off
	v_lshl_add_u64 v[168:169], s[16:17], 0, v[138:139]
	s_add_i32 m0, s28, 0xe000
	s_nop 0
	global_load_lds_dwordx4 v[168:169], off
	s_waitcnt lgkmcnt(8)
	s_barrier
	s_waitcnt lgkmcnt(0)
	s_setprio 1
	s_waitcnt lgkmcnt(0)
	v_mfma_f32_16x16x32_bf16 v[124:127], v[152:155], v[172:175], v[124:127]
	v_mfma_f32_16x16x32_bf16 v[120:123], v[160:163], v[172:175], v[120:123]
	v_mfma_f32_16x16x32_bf16 v[116:119], v[152:155], v[180:183], v[116:119]
	v_mfma_f32_16x16x32_bf16 v[108:111], v[160:163], v[180:183], v[108:111]
	v_mfma_f32_16x16x32_bf16 v[100:103], v[152:155], v[188:191], v[100:103]
	v_mfma_f32_16x16x32_bf16 v[92:95], v[160:163], v[188:191], v[92:95]
	v_mfma_f32_16x16x32_bf16 v[84:87], v[152:155], v[196:199], v[84:87]
	v_mfma_f32_16x16x32_bf16 v[76:79], v[160:163], v[196:199], v[76:79]
	v_mfma_f32_16x16x32_bf16 v[124:127], v[156:159], v[176:179], v[124:127]
	v_mfma_f32_16x16x32_bf16 v[120:123], v[164:167], v[176:179], v[120:123]
	v_mfma_f32_16x16x32_bf16 v[116:119], v[156:159], v[184:187], v[116:119]
	v_mfma_f32_16x16x32_bf16 v[108:111], v[164:167], v[184:187], v[108:111]
	v_mfma_f32_16x16x32_bf16 v[100:103], v[156:159], v[192:195], v[100:103]
	v_mfma_f32_16x16x32_bf16 v[92:95], v[164:167], v[192:195], v[92:95]
	v_mfma_f32_16x16x32_bf16 v[84:87], v[156:159], v[200:203], v[84:87]
	v_mfma_f32_16x16x32_bf16 v[76:79], v[164:167], v[200:203], v[76:79]
	s_setprio 0
	s_barrier
	s_add_i32 s16, s36, s27
	v_lshl_add_u64 v[168:169], s[18:19], 0, v[132:133]
	s_mov_b32 m0, s16
	ds_read_b128 v[204:207], v151
	ds_read_b128 v[208:211], v151 offset:1024
	ds_read_b128 v[212:215], v151 offset:2048
	ds_read_b128 v[216:219], v151 offset:3072
	global_load_lds_dwordx4 v[168:169], off
	v_lshl_add_u64 v[220:221], s[18:19], 0, v[128:129]
	s_add_i32 m0, s16, 0x2000
	s_nop 0
	global_load_lds_dwordx4 v[220:221], off
	s_barrier
	s_waitcnt lgkmcnt(0)
	s_setprio 1
	s_waitcnt lgkmcnt(0)
	v_mfma_f32_16x16x32_bf16 v[112:115], v[204:207], v[172:175], v[112:115]
	v_mfma_f32_16x16x32_bf16 v[104:107], v[212:215], v[172:175], v[104:107]
	v_mfma_f32_16x16x32_bf16 v[96:99], v[204:207], v[180:183], v[96:99]
	v_mfma_f32_16x16x32_bf16 v[88:91], v[212:215], v[180:183], v[88:91]
	v_mfma_f32_16x16x32_bf16 v[80:83], v[204:207], v[188:191], v[80:83]
	v_mfma_f32_16x16x32_bf16 v[72:75], v[212:215], v[188:191], v[72:75]
	v_mfma_f32_16x16x32_bf16 v[68:71], v[204:207], v[196:199], v[68:71]
	v_mfma_f32_16x16x32_bf16 v[64:67], v[212:215], v[196:199], v[64:67]
	v_mfma_f32_16x16x32_bf16 v[112:115], v[208:211], v[176:179], v[112:115]
	v_mfma_f32_16x16x32_bf16 v[104:107], v[216:219], v[176:179], v[104:107]
	v_mfma_f32_16x16x32_bf16 v[96:99], v[208:211], v[184:187], v[96:99]
	v_mfma_f32_16x16x32_bf16 v[88:91], v[216:219], v[184:187], v[88:91]
	v_mfma_f32_16x16x32_bf16 v[80:83], v[208:211], v[192:195], v[80:83]
	v_mfma_f32_16x16x32_bf16 v[72:75], v[216:219], v[192:195], v[72:75]
	v_mfma_f32_16x16x32_bf16 v[68:71], v[208:211], v[200:203], v[68:71]
	v_mfma_f32_16x16x32_bf16 v[64:67], v[216:219], v[200:203], v[64:67]
	s_setprio 0
	s_mov_b32 m0, s28
	v_lshl_add_u64 v[222:223], s[20:21], 0, v[134:135]
	s_barrier
	ds_read_b128 v[172:175], v150 offset:16384
	ds_read_b128 v[176:179], v150 offset:17408
	ds_read_b128 v[180:183], v150 offset:18432
	ds_read_b128 v[184:187], v150 offset:19456
	ds_read_b128 v[188:191], v150 offset:20480
	ds_read_b128 v[192:195], v150 offset:21504
	ds_read_b128 v[196:199], v150 offset:22528
	ds_read_b128 v[200:203], v150 offset:23552
	global_load_lds_dwordx4 v[222:223], off
	v_lshl_add_u64 v[224:225], s[20:21], 0, v[130:131]
	s_mov_b32 m0, s29
	s_nop 0
	global_load_lds_dwordx4 v[224:225], off
	s_barrier
	s_waitcnt lgkmcnt(0)
	s_setprio 1
	s_waitcnt lgkmcnt(0)
	v_mfma_f32_16x16x32_bf16 v[60:63], v[152:155], v[172:175], v[60:63]
	v_mfma_f32_16x16x32_bf16 v[56:59], v[160:163], v[172:175], v[56:59]
	v_mfma_f32_16x16x32_bf16 v[52:55], v[152:155], v[180:183], v[52:55]
	v_mfma_f32_16x16x32_bf16 v[44:47], v[160:163], v[180:183], v[44:47]
	v_mfma_f32_16x16x32_bf16 v[36:39], v[152:155], v[188:191], v[36:39]
	v_mfma_f32_16x16x32_bf16 v[28:31], v[160:163], v[188:191], v[28:31]
	v_mfma_f32_16x16x32_bf16 v[20:23], v[152:155], v[196:199], v[20:23]
	v_mfma_f32_16x16x32_bf16 v[12:15], v[160:163], v[196:199], v[12:15]
	v_mfma_f32_16x16x32_bf16 v[60:63], v[156:159], v[176:179], v[60:63]
	v_mfma_f32_16x16x32_bf16 v[56:59], v[164:167], v[176:179], v[56:59]
	v_mfma_f32_16x16x32_bf16 v[52:55], v[156:159], v[184:187], v[52:55]
	v_mfma_f32_16x16x32_bf16 v[44:47], v[164:167], v[184:187], v[44:47]
	v_mfma_f32_16x16x32_bf16 v[36:39], v[156:159], v[192:195], v[36:39]
	v_mfma_f32_16x16x32_bf16 v[28:31], v[164:167], v[192:195], v[28:31]
	v_mfma_f32_16x16x32_bf16 v[20:23], v[156:159], v[200:203], v[20:23]
	v_mfma_f32_16x16x32_bf16 v[12:15], v[164:167], v[200:203], v[12:15]
	s_setprio 0
	s_barrier
	s_add_u32 s16, s18, 0x40000
	s_addc_u32 s17, s19, 0
	s_add_i32 s46, s37, s27
	v_lshl_add_u64 v[152:153], s[16:17], 0, v[132:133]
	s_mov_b32 m0, s46
	s_nop 0
	global_load_lds_dwordx4 v[152:153], off
	v_lshl_add_u64 v[152:153], s[16:17], 0, v[128:129]
	s_add_i32 m0, s46, 0x2000
	s_nop 0
	global_load_lds_dwordx4 v[152:153], off
	s_waitcnt vmcnt(6)
	s_barrier
	s_setprio 1
	v_mfma_f32_16x16x32_bf16 v[48:51], v[204:207], v[172:175], v[48:51]
	v_mfma_f32_16x16x32_bf16 v[40:43], v[212:215], v[172:175], v[40:43]
	v_mfma_f32_16x16x32_bf16 v[32:35], v[204:207], v[180:183], v[32:35]
	v_mfma_f32_16x16x32_bf16 v[24:27], v[212:215], v[180:183], v[24:27]
	v_mfma_f32_16x16x32_bf16 v[16:19], v[204:207], v[188:191], v[16:19]
	v_mfma_f32_16x16x32_bf16 v[8:11], v[212:215], v[188:191], v[8:11]
	v_mfma_f32_16x16x32_bf16 v[4:7], v[204:207], v[196:199], v[4:7]
	v_mfma_f32_16x16x32_bf16 v[0:3], v[212:215], v[196:199], v[0:3]
	v_mfma_f32_16x16x32_bf16 v[48:51], v[208:211], v[176:179], v[48:51]
	v_mfma_f32_16x16x32_bf16 v[40:43], v[216:219], v[176:179], v[40:43]
	v_mfma_f32_16x16x32_bf16 v[32:35], v[208:211], v[184:187], v[32:35]
	v_mfma_f32_16x16x32_bf16 v[24:27], v[216:219], v[184:187], v[24:27]
	v_mfma_f32_16x16x32_bf16 v[16:19], v[208:211], v[192:195], v[16:19]
	v_mfma_f32_16x16x32_bf16 v[8:11], v[216:219], v[192:195], v[8:11]
	v_mfma_f32_16x16x32_bf16 v[4:7], v[208:211], v[200:203], v[4:7]
	v_mfma_f32_16x16x32_bf16 v[0:3], v[216:219], v[200:203], v[0:3]
	s_setprio 0
	s_add_i32 s46, 0, 0x18000
	v_add_u32_e32 v164, s46, v148
	s_barrier
	ds_read_b128 v[152:155], v164
	ds_read_b128 v[156:159], v164 offset:1024
	ds_read_b128 v[160:163], v164 offset:2048
	ds_read_b128 v[164:167], v164 offset:3072
	s_add_u32 s16, s20, 0xea000
	s_addc_u32 s17, s21, 0
	s_mov_b32 m0, s30
	v_lshl_add_u64 v[204:205], s[16:17], 0, v[134:135]
	ds_read_b128 v[172:175], v150 offset:32768
	ds_read_b128 v[176:179], v150 offset:33792
	ds_read_b128 v[180:183], v150 offset:34816
	ds_read_b128 v[184:187], v150 offset:35840
	ds_read_b128 v[188:191], v150 offset:36864
	ds_read_b128 v[192:195], v150 offset:37888
	ds_read_b128 v[196:199], v150 offset:38912
	ds_read_b128 v[200:203], v150 offset:39936
	global_load_lds_dwordx4 v[204:205], off
	v_lshl_add_u64 v[204:205], s[16:17], 0, v[130:131]
	s_mov_b32 m0, s31
	s_nop 0
	global_load_lds_dwordx4 v[204:205], off
	s_waitcnt lgkmcnt(8)
	s_barrier
	s_waitcnt lgkmcnt(0)
	s_setprio 1
	s_waitcnt lgkmcnt(0)
	v_mfma_f32_16x16x32_bf16 v[124:127], v[152:155], v[172:175], v[124:127]
	v_mfma_f32_16x16x32_bf16 v[120:123], v[160:163], v[172:175], v[120:123]
	v_mfma_f32_16x16x32_bf16 v[116:119], v[152:155], v[180:183], v[116:119]
	v_mfma_f32_16x16x32_bf16 v[108:111], v[160:163], v[180:183], v[108:111]
	v_mfma_f32_16x16x32_bf16 v[100:103], v[152:155], v[188:191], v[100:103]
	v_mfma_f32_16x16x32_bf16 v[92:95], v[160:163], v[188:191], v[92:95]
	v_mfma_f32_16x16x32_bf16 v[84:87], v[152:155], v[196:199], v[84:87]
	v_mfma_f32_16x16x32_bf16 v[76:79], v[160:163], v[196:199], v[76:79]
	v_mfma_f32_16x16x32_bf16 v[124:127], v[156:159], v[176:179], v[124:127]
	v_mfma_f32_16x16x32_bf16 v[120:123], v[164:167], v[176:179], v[120:123]
	v_mfma_f32_16x16x32_bf16 v[116:119], v[156:159], v[184:187], v[116:119]
	v_mfma_f32_16x16x32_bf16 v[108:111], v[164:167], v[184:187], v[108:111]
	v_mfma_f32_16x16x32_bf16 v[100:103], v[156:159], v[192:195], v[100:103]
	v_mfma_f32_16x16x32_bf16 v[92:95], v[164:167], v[192:195], v[92:95]
	v_mfma_f32_16x16x32_bf16 v[84:87], v[156:159], v[200:203], v[84:87]
	v_mfma_f32_16x16x32_bf16 v[76:79], v[164:167], v[200:203], v[76:79]
	s_setprio 0
	s_barrier
	s_add_i32 s20, 0, 0x1c000
	s_add_i32 s16, s46, s27
	v_add_u32_e32 v171, s20, v148
	v_lshl_add_u64 v[168:169], v[168:169], 0, s[4:5]
	s_mov_b32 m0, s16
	ds_read_b128 v[204:207], v171
	ds_read_b128 v[208:211], v171 offset:1024
	ds_read_b128 v[212:215], v171 offset:2048
	ds_read_b128 v[216:219], v171 offset:3072
	global_load_lds_dwordx4 v[168:169], off
	v_lshl_add_u64 v[168:169], v[220:221], 0, s[4:5]
	s_add_i32 m0, s16, 0x2000
	s_nop 0
	global_load_lds_dwordx4 v[168:169], off
	s_barrier
	s_waitcnt lgkmcnt(0)
	s_setprio 1
	s_waitcnt lgkmcnt(0)
	v_mfma_f32_16x16x32_bf16 v[112:115], v[204:207], v[172:175], v[112:115]
	v_mfma_f32_16x16x32_bf16 v[104:107], v[212:215], v[172:175], v[104:107]
	v_mfma_f32_16x16x32_bf16 v[96:99], v[204:207], v[180:183], v[96:99]
	v_mfma_f32_16x16x32_bf16 v[88:91], v[212:215], v[180:183], v[88:91]
	v_mfma_f32_16x16x32_bf16 v[80:83], v[204:207], v[188:191], v[80:83]
	v_mfma_f32_16x16x32_bf16 v[72:75], v[212:215], v[188:191], v[72:75]
	v_mfma_f32_16x16x32_bf16 v[68:71], v[204:207], v[196:199], v[68:71]
	v_mfma_f32_16x16x32_bf16 v[64:67], v[212:215], v[196:199], v[64:67]
	v_mfma_f32_16x16x32_bf16 v[112:115], v[208:211], v[176:179], v[112:115]
	v_mfma_f32_16x16x32_bf16 v[104:107], v[216:219], v[176:179], v[104:107]
	v_mfma_f32_16x16x32_bf16 v[96:99], v[208:211], v[184:187], v[96:99]
	v_mfma_f32_16x16x32_bf16 v[88:91], v[216:219], v[184:187], v[88:91]
	v_mfma_f32_16x16x32_bf16 v[80:83], v[208:211], v[192:195], v[80:83]
	v_mfma_f32_16x16x32_bf16 v[72:75], v[216:219], v[192:195], v[72:75]
	v_mfma_f32_16x16x32_bf16 v[68:71], v[208:211], v[200:203], v[68:71]
	v_mfma_f32_16x16x32_bf16 v[64:67], v[216:219], v[200:203], v[64:67]
	s_setprio 0
	s_mov_b32 m0, s33
	v_lshl_add_u64 v[168:169], v[222:223], 0, s[4:5]
	s_barrier
	ds_read_b128 v[172:175], v150 offset:49152
	ds_read_b128 v[176:179], v150 offset:50176
	ds_read_b128 v[180:183], v150 offset:51200
	ds_read_b128 v[184:187], v150 offset:52224
	ds_read_b128 v[188:191], v150 offset:53248
	ds_read_b128 v[192:195], v150 offset:54272
	ds_read_b128 v[196:199], v150 offset:55296
	ds_read_b128 v[200:203], v150 offset:56320
	global_load_lds_dwordx4 v[168:169], off
	v_lshl_add_u64 v[168:169], v[224:225], 0, s[4:5]
	s_mov_b32 m0, s34
	s_nop 0
	global_load_lds_dwordx4 v[168:169], off
	s_barrier
	s_waitcnt lgkmcnt(0)
	s_setprio 1
	s_waitcnt lgkmcnt(0)
	v_mfma_f32_16x16x32_bf16 v[60:63], v[152:155], v[172:175], v[60:63]
	v_mfma_f32_16x16x32_bf16 v[56:59], v[160:163], v[172:175], v[56:59]
	v_mfma_f32_16x16x32_bf16 v[52:55], v[152:155], v[180:183], v[52:55]
	v_mfma_f32_16x16x32_bf16 v[44:47], v[160:163], v[180:183], v[44:47]
	v_mfma_f32_16x16x32_bf16 v[36:39], v[152:155], v[188:191], v[36:39]
	v_mfma_f32_16x16x32_bf16 v[28:31], v[160:163], v[188:191], v[28:31]
	v_mfma_f32_16x16x32_bf16 v[20:23], v[152:155], v[196:199], v[20:23]
	v_mfma_f32_16x16x32_bf16 v[12:15], v[160:163], v[196:199], v[12:15]
	v_mfma_f32_16x16x32_bf16 v[60:63], v[156:159], v[176:179], v[60:63]
	v_mfma_f32_16x16x32_bf16 v[56:59], v[164:167], v[176:179], v[56:59]
	v_mfma_f32_16x16x32_bf16 v[52:55], v[156:159], v[184:187], v[52:55]
	v_mfma_f32_16x16x32_bf16 v[44:47], v[164:167], v[184:187], v[44:47]
	v_mfma_f32_16x16x32_bf16 v[36:39], v[156:159], v[192:195], v[36:39]
	v_mfma_f32_16x16x32_bf16 v[28:31], v[164:167], v[192:195], v[28:31]
	v_mfma_f32_16x16x32_bf16 v[20:23], v[156:159], v[200:203], v[20:23]
	v_mfma_f32_16x16x32_bf16 v[12:15], v[164:167], v[200:203], v[12:15]
	s_setprio 0
	s_barrier
	s_add_u32 s16, s18, 0x40080
	s_addc_u32 s17, s19, 0
	s_add_i32 s18, s20, s27
	v_lshl_add_u64 v[152:153], s[16:17], 0, v[132:133]
	s_mov_b32 m0, s18
	s_nop 0
	global_load_lds_dwordx4 v[152:153], off
	v_lshl_add_u64 v[152:153], s[16:17], 0, v[128:129]
	s_add_i32 m0, s18, 0x2000
	s_nop 0
	global_load_lds_dwordx4 v[152:153], off
	s_waitcnt vmcnt(6)
	s_barrier
	s_setprio 1
	v_mfma_f32_16x16x32_bf16 v[48:51], v[204:207], v[172:175], v[48:51]
	v_mfma_f32_16x16x32_bf16 v[40:43], v[212:215], v[172:175], v[40:43]
	v_mfma_f32_16x16x32_bf16 v[32:35], v[204:207], v[180:183], v[32:35]
	v_mfma_f32_16x16x32_bf16 v[24:27], v[212:215], v[180:183], v[24:27]
	v_mfma_f32_16x16x32_bf16 v[16:19], v[204:207], v[188:191], v[16:19]
	v_mfma_f32_16x16x32_bf16 v[8:11], v[212:215], v[188:191], v[8:11]
	v_mfma_f32_16x16x32_bf16 v[4:7], v[204:207], v[196:199], v[4:7]
	v_mfma_f32_16x16x32_bf16 v[0:3], v[212:215], v[196:199], v[0:3]
	v_mfma_f32_16x16x32_bf16 v[48:51], v[208:211], v[176:179], v[48:51]
	v_mfma_f32_16x16x32_bf16 v[40:43], v[216:219], v[176:179], v[40:43]
	v_mfma_f32_16x16x32_bf16 v[32:35], v[208:211], v[184:187], v[32:35]
	v_mfma_f32_16x16x32_bf16 v[24:27], v[216:219], v[184:187], v[24:27]
	v_mfma_f32_16x16x32_bf16 v[16:19], v[208:211], v[192:195], v[16:19]
	v_mfma_f32_16x16x32_bf16 v[8:11], v[216:219], v[192:195], v[8:11]
	v_mfma_f32_16x16x32_bf16 v[4:7], v[208:211], v[200:203], v[4:7]
	v_mfma_f32_16x16x32_bf16 v[0:3], v[216:219], v[200:203], v[0:3]
	s_setprio 0
	s_add_i32 s45, s45, 2
	s_add_u32 s43, s43, 0x100
	s_addc_u32 s44, s44, 0
	s_cmp_gt_u32 s45, 13
	s_mov_b64 s[16:17], s[8:9]
	s_barrier
	s_cbranch_scc0 .LBB0_2046
	v_lshl_add_u32 v152, s41, 8, v147
	s_lshl_b32 s8, s40, 8
	v_ashrrev_i32_e32 v153, 31, v152
	s_ashr_i32 s9, s8, 31
	v_lshlrev_b64 v[154:155], 11, v[152:153]
	v_lshl_add_u64 v[154:155], s[0:1], 0, v[154:155]
	s_lshl_b64 s[8:9], s[8:9], 1
	v_lshl_add_u64 v[154:155], v[154:155], 0, s[8:9]
	v_lshl_add_u64 v[154:155], v[154:155], 0, s[2:3]
	v_lshl_add_u64 v[154:155], v[154:155], 0, v[136:137]
	v_mbcnt_lo_u32_b32 v237, -1, 0
	v_mbcnt_hi_u32_b32 v237, -1, v237
	v_bfe_i32 v237, v237, 4, 1
	v_and_b32_e32 v244, 24, v237
	v_add_co_u32_e32 v248, vcc, v244, v154
	s_nop 1
	v_addc_co_u32_e32 v249, vcc, 0, v155, vcc
	v_cvt_pk_bf16_f32 v124, v124, v125
	v_cvt_pk_bf16_f32 v125, v126, v127
	v_cvt_pk_bf16_f32 v120, v120, v121
	v_cvt_pk_bf16_f32 v121, v122, v123
	v_bfi_b32 v244, v237, v124, v120
	v_bfi_b32 v245, v237, v125, v121
	ds_swizzle_b32 v250, v244 offset:0x401f
	ds_swizzle_b32 v251, v245 offset:0x401f
	v_cvt_pk_bf16_f32 v112, v112, v113
	v_cvt_pk_bf16_f32 v113, v114, v115
	v_cvt_pk_bf16_f32 v104, v104, v105
	v_cvt_pk_bf16_f32 v105, v106, v107
	v_bfi_b32 v246, v237, v112, v104
	v_bfi_b32 v247, v237, v113, v105
	ds_swizzle_b32 v252, v246 offset:0x401f
	ds_swizzle_b32 v253, v247 offset:0x401f
	s_waitcnt lgkmcnt(0)
	v_bfi_b32 v240, v237, v250, v124
	v_bfi_b32 v241, v237, v251, v125
	v_bfi_b32 v242, v237, v120, v250
	v_bfi_b32 v243, v237, v121, v251
	global_store_dwordx4 v[248:249], v[240:243], off
	s_nop 1
	v_bfi_b32 v240, v237, v252, v112
	v_bfi_b32 v241, v237, v253, v113
	v_bfi_b32 v242, v237, v104, v252
	v_bfi_b32 v243, v237, v105, v253
	global_store_dwordx4 v[248:249], v[240:243], off offset:256
	s_nop 1
	v_add_co_u32_e32 v238, vcc, 0x8000, v248
	s_nop 1
	v_addc_co_u32_e32 v239, vcc, 0, v249, vcc
	v_cvt_pk_bf16_f32 v116, v116, v117
	v_cvt_pk_bf16_f32 v117, v118, v119
	v_cvt_pk_bf16_f32 v108, v108, v109
	v_cvt_pk_bf16_f32 v109, v110, v111
	v_bfi_b32 v244, v237, v116, v108
	v_bfi_b32 v245, v237, v117, v109
	ds_swizzle_b32 v250, v244 offset:0x401f
	ds_swizzle_b32 v251, v245 offset:0x401f
	v_cvt_pk_bf16_f32 v96, v96, v97
	v_cvt_pk_bf16_f32 v97, v98, v99
	v_cvt_pk_bf16_f32 v88, v88, v89
	v_cvt_pk_bf16_f32 v89, v90, v91
	v_bfi_b32 v246, v237, v96, v88
	v_bfi_b32 v247, v237, v97, v89
	ds_swizzle_b32 v252, v246 offset:0x401f
	ds_swizzle_b32 v253, v247 offset:0x401f
	s_waitcnt lgkmcnt(0)
	v_bfi_b32 v240, v237, v250, v116
	v_bfi_b32 v241, v237, v251, v117
	v_bfi_b32 v242, v237, v108, v250
	v_bfi_b32 v243, v237, v109, v251
	global_store_dwordx4 v[238:239], v[240:243], off
	s_nop 1
	v_bfi_b32 v240, v237, v252, v96
	v_bfi_b32 v241, v237, v253, v97
	v_bfi_b32 v242, v237, v88, v252
	v_bfi_b32 v243, v237, v89, v253
	global_store_dwordx4 v[238:239], v[240:243], off offset:256
	s_nop 1
	v_add_co_u32_e32 v238, vcc, 0x10000, v248
	s_nop 1
	v_addc_co_u32_e32 v239, vcc, 0, v249, vcc
	v_cvt_pk_bf16_f32 v100, v100, v101
	v_cvt_pk_bf16_f32 v101, v102, v103
	v_cvt_pk_bf16_f32 v92, v92, v93
	v_cvt_pk_bf16_f32 v93, v94, v95
	v_bfi_b32 v244, v237, v100, v92
	v_bfi_b32 v245, v237, v101, v93
	ds_swizzle_b32 v250, v244 offset:0x401f
	ds_swizzle_b32 v251, v245 offset:0x401f
	v_cvt_pk_bf16_f32 v80, v80, v81
	v_cvt_pk_bf16_f32 v81, v82, v83
	v_cvt_pk_bf16_f32 v72, v72, v73
	v_cvt_pk_bf16_f32 v73, v74, v75
	v_bfi_b32 v246, v237, v80, v72
	v_bfi_b32 v247, v237, v81, v73
	ds_swizzle_b32 v252, v246 offset:0x401f
	ds_swizzle_b32 v253, v247 offset:0x401f
	s_waitcnt lgkmcnt(0)
	v_bfi_b32 v240, v237, v250, v100
	v_bfi_b32 v241, v237, v251, v101
	v_bfi_b32 v242, v237, v92, v250
	v_bfi_b32 v243, v237, v93, v251
	global_store_dwordx4 v[238:239], v[240:243], off
	s_nop 1
	v_bfi_b32 v240, v237, v252, v80
	v_bfi_b32 v241, v237, v253, v81
	v_bfi_b32 v242, v237, v72, v252
	v_bfi_b32 v243, v237, v73, v253
	global_store_dwordx4 v[238:239], v[240:243], off offset:256
	s_nop 1
	v_add_co_u32_e32 v238, vcc, 0x18000, v248
	s_nop 1
	v_addc_co_u32_e32 v239, vcc, 0, v249, vcc
	v_cvt_pk_bf16_f32 v84, v84, v85
	v_cvt_pk_bf16_f32 v85, v86, v87
	v_cvt_pk_bf16_f32 v76, v76, v77
	v_cvt_pk_bf16_f32 v77, v78, v79
	v_bfi_b32 v244, v237, v84, v76
	v_bfi_b32 v245, v237, v85, v77
	ds_swizzle_b32 v250, v244 offset:0x401f
	ds_swizzle_b32 v251, v245 offset:0x401f
	v_cvt_pk_bf16_f32 v68, v68, v69
	v_cvt_pk_bf16_f32 v69, v70, v71
	v_cvt_pk_bf16_f32 v64, v64, v65
	v_cvt_pk_bf16_f32 v65, v66, v67
	v_bfi_b32 v246, v237, v68, v64
	v_bfi_b32 v247, v237, v69, v65
	ds_swizzle_b32 v252, v246 offset:0x401f
	ds_swizzle_b32 v253, v247 offset:0x401f
	s_waitcnt lgkmcnt(0)
	v_bfi_b32 v240, v237, v250, v84
	v_bfi_b32 v241, v237, v251, v85
	v_bfi_b32 v242, v237, v76, v250
	v_bfi_b32 v243, v237, v77, v251
	global_store_dwordx4 v[238:239], v[240:243], off
	s_nop 1
	v_bfi_b32 v240, v237, v252, v68
	v_bfi_b32 v241, v237, v253, v69
	v_bfi_b32 v242, v237, v64, v252
	v_bfi_b32 v243, v237, v65, v253
	global_store_dwordx4 v[238:239], v[240:243], off offset:256
	s_nop 1
	v_add_co_u32_e32 v238, vcc, 0x40000, v248
	s_nop 1
	v_addc_co_u32_e32 v239, vcc, 0, v249, vcc
	v_cvt_pk_bf16_f32 v60, v60, v61
	v_cvt_pk_bf16_f32 v61, v62, v63
	v_cvt_pk_bf16_f32 v56, v56, v57
	v_cvt_pk_bf16_f32 v57, v58, v59
	v_bfi_b32 v244, v237, v60, v56
	v_bfi_b32 v245, v237, v61, v57
	ds_swizzle_b32 v250, v244 offset:0x401f
	ds_swizzle_b32 v251, v245 offset:0x401f
	v_cvt_pk_bf16_f32 v48, v48, v49
	v_cvt_pk_bf16_f32 v49, v50, v51
	v_cvt_pk_bf16_f32 v40, v40, v41
	v_cvt_pk_bf16_f32 v41, v42, v43
	v_bfi_b32 v246, v237, v48, v40
	v_bfi_b32 v247, v237, v49, v41
	ds_swizzle_b32 v252, v246 offset:0x401f
	ds_swizzle_b32 v253, v247 offset:0x401f
	s_waitcnt lgkmcnt(0)
	v_bfi_b32 v240, v237, v250, v60
	v_bfi_b32 v241, v237, v251, v61
	v_bfi_b32 v242, v237, v56, v250
	v_bfi_b32 v243, v237, v57, v251
	global_store_dwordx4 v[238:239], v[240:243], off
	s_nop 1
	v_bfi_b32 v240, v237, v252, v48
	v_bfi_b32 v241, v237, v253, v49
	v_bfi_b32 v242, v237, v40, v252
	v_bfi_b32 v243, v237, v41, v253
	global_store_dwordx4 v[238:239], v[240:243], off offset:256
	s_nop 1
	v_add_co_u32_e32 v238, vcc, 0x48000, v248
	s_nop 1
	v_addc_co_u32_e32 v239, vcc, 0, v249, vcc
	v_cvt_pk_bf16_f32 v52, v52, v53
	v_cvt_pk_bf16_f32 v53, v54, v55
	v_cvt_pk_bf16_f32 v44, v44, v45
	v_cvt_pk_bf16_f32 v45, v46, v47
	v_bfi_b32 v244, v237, v52, v44
	v_bfi_b32 v245, v237, v53, v45
	ds_swizzle_b32 v250, v244 offset:0x401f
	ds_swizzle_b32 v251, v245 offset:0x401f
	v_cvt_pk_bf16_f32 v32, v32, v33
	v_cvt_pk_bf16_f32 v33, v34, v35
	v_cvt_pk_bf16_f32 v24, v24, v25
	v_cvt_pk_bf16_f32 v25, v26, v27
	v_bfi_b32 v246, v237, v32, v24
	v_bfi_b32 v247, v237, v33, v25
	ds_swizzle_b32 v252, v246 offset:0x401f
	ds_swizzle_b32 v253, v247 offset:0x401f
	s_waitcnt lgkmcnt(0)
	v_bfi_b32 v240, v237, v250, v52
	v_bfi_b32 v241, v237, v251, v53
	v_bfi_b32 v242, v237, v44, v250
	v_bfi_b32 v243, v237, v45, v251
	global_store_dwordx4 v[238:239], v[240:243], off
	s_nop 1
	v_bfi_b32 v240, v237, v252, v32
	v_bfi_b32 v241, v237, v253, v33
	v_bfi_b32 v242, v237, v24, v252
	v_bfi_b32 v243, v237, v25, v253
	global_store_dwordx4 v[238:239], v[240:243], off offset:256
	s_nop 1
	v_add_co_u32_e32 v238, vcc, 0x50000, v248
	s_nop 1
	v_addc_co_u32_e32 v239, vcc, 0, v249, vcc
	v_cvt_pk_bf16_f32 v36, v36, v37
	v_cvt_pk_bf16_f32 v37, v38, v39
	v_cvt_pk_bf16_f32 v28, v28, v29
	v_cvt_pk_bf16_f32 v29, v30, v31
	v_bfi_b32 v244, v237, v36, v28
	v_bfi_b32 v245, v237, v37, v29
	ds_swizzle_b32 v250, v244 offset:0x401f
	ds_swizzle_b32 v251, v245 offset:0x401f
	v_cvt_pk_bf16_f32 v16, v16, v17
	v_cvt_pk_bf16_f32 v17, v18, v19
	v_cvt_pk_bf16_f32 v8, v8, v9
	v_cvt_pk_bf16_f32 v9, v10, v11
	v_bfi_b32 v246, v237, v16, v8
	v_bfi_b32 v247, v237, v17, v9
	ds_swizzle_b32 v252, v246 offset:0x401f
	ds_swizzle_b32 v253, v247 offset:0x401f
	s_waitcnt lgkmcnt(0)
	v_bfi_b32 v240, v237, v250, v36
	v_bfi_b32 v241, v237, v251, v37
	v_bfi_b32 v242, v237, v28, v250
	v_bfi_b32 v243, v237, v29, v251
	global_store_dwordx4 v[238:239], v[240:243], off
	s_nop 1
	v_bfi_b32 v240, v237, v252, v16
	v_bfi_b32 v241, v237, v253, v17
	v_bfi_b32 v242, v237, v8, v252
	v_bfi_b32 v243, v237, v9, v253
	global_store_dwordx4 v[238:239], v[240:243], off offset:256
	s_nop 1
	v_add_co_u32_e32 v238, vcc, 0x58000, v248
	s_nop 1
	v_addc_co_u32_e32 v239, vcc, 0, v249, vcc
	v_cvt_pk_bf16_f32 v20, v20, v21
	v_cvt_pk_bf16_f32 v21, v22, v23
	v_cvt_pk_bf16_f32 v12, v12, v13
	v_cvt_pk_bf16_f32 v13, v14, v15
	v_bfi_b32 v244, v237, v20, v12
	v_bfi_b32 v245, v237, v21, v13
	ds_swizzle_b32 v250, v244 offset:0x401f
	ds_swizzle_b32 v251, v245 offset:0x401f
	v_cvt_pk_bf16_f32 v4, v4, v5
	v_cvt_pk_bf16_f32 v5, v6, v7
	v_cvt_pk_bf16_f32 v0, v0, v1
	v_cvt_pk_bf16_f32 v1, v2, v3
	v_bfi_b32 v246, v237, v4, v0
	v_bfi_b32 v247, v237, v5, v1
	ds_swizzle_b32 v252, v246 offset:0x401f
	ds_swizzle_b32 v253, v247 offset:0x401f
	s_waitcnt lgkmcnt(0)
	v_bfi_b32 v240, v237, v250, v20
	v_bfi_b32 v241, v237, v251, v21
	v_bfi_b32 v242, v237, v12, v250
	v_bfi_b32 v243, v237, v13, v251
	global_store_dwordx4 v[238:239], v[240:243], off
	s_nop 1
	v_bfi_b32 v240, v237, v252, v4
	v_bfi_b32 v241, v237, v253, v5
	v_bfi_b32 v242, v237, v0, v252
	v_bfi_b32 v243, v237, v1, v253
	global_store_dwordx4 v[238:239], v[240:243], off offset:256
	s_nop 1
	s_and_b64 vcc, exec, s[6:7]
	s_mov_b32 s40, s10
	s_mov_b32 s41, s39
	s_mov_b64 s[18:19], s[14:15]
	s_mov_b64 s[16:17], s[12:13]
	s_cbranch_vccz .LBB0_2041
	s_waitcnt vmcnt(0)
	s_cmpk_gt_u32 s22, 0xff
	s_cbranch_scc1 .LBB0_2050
	s_barrier

.LBB0_2279:
	ds_read_b128 v[148:151], v145
	ds_read_b128 v[152:155], v145 offset:1024
	ds_read_b128 v[156:159], v145 offset:2048
	ds_read_b128 v[160:163], v145 offset:3072
	s_add_u32 s14, s12, 0x100
	s_addc_u32 s15, s13, 0
	s_cmp_eq_u32 s43, 40
	s_cselect_b32 s19, s7, s15
	s_cselect_b32 s18, s6, s14
	s_cselect_b32 s17, s1, s42
	s_cselect_b32 s16, s0, s41
	s_mov_b32 m0, s36
	v_lshl_add_u64 v[168:169], s[12:13], 0, v[136:137]
	ds_read_b128 v[164:167], v146
	ds_read_b128 v[172:175], v146 offset:1024
	ds_read_b128 v[176:179], v146 offset:2048
	ds_read_b128 v[180:183], v146 offset:3072
	ds_read_b128 v[184:187], v146 offset:4096
	ds_read_b128 v[188:191], v146 offset:5120
	ds_read_b128 v[192:195], v146 offset:6144
	ds_read_b128 v[196:199], v146 offset:7168
	global_load_lds_dwordx4 v[168:169], off
	v_lshl_add_u64 v[168:169], s[12:13], 0, v[134:135]
	s_mov_b32 m0, s37
	s_nop 0
	global_load_lds_dwordx4 v[168:169], off
	s_waitcnt lgkmcnt(8)
	s_barrier
	s_waitcnt lgkmcnt(0)
	s_setprio 1
	s_waitcnt lgkmcnt(0)
	v_mfma_f32_16x16x32_bf16 v[124:127], v[148:151], v[164:167], v[124:127]
	v_mfma_f32_16x16x32_bf16 v[120:123], v[156:159], v[164:167], v[120:123]
	v_mfma_f32_16x16x32_bf16 v[116:119], v[148:151], v[176:179], v[116:119]
	v_mfma_f32_16x16x32_bf16 v[108:111], v[156:159], v[176:179], v[108:111]
	v_mfma_f32_16x16x32_bf16 v[100:103], v[148:151], v[184:187], v[100:103]
	v_mfma_f32_16x16x32_bf16 v[92:95], v[156:159], v[184:187], v[92:95]
	v_mfma_f32_16x16x32_bf16 v[84:87], v[148:151], v[192:195], v[84:87]
	v_mfma_f32_16x16x32_bf16 v[76:79], v[156:159], v[192:195], v[76:79]
	v_mfma_f32_16x16x32_bf16 v[124:127], v[152:155], v[172:175], v[124:127]
	v_mfma_f32_16x16x32_bf16 v[120:123], v[160:163], v[172:175], v[120:123]
	v_mfma_f32_16x16x32_bf16 v[116:119], v[152:155], v[180:183], v[116:119]
	v_mfma_f32_16x16x32_bf16 v[108:111], v[160:163], v[180:183], v[108:111]
	v_mfma_f32_16x16x32_bf16 v[100:103], v[152:155], v[188:191], v[100:103]
	v_mfma_f32_16x16x32_bf16 v[92:95], v[160:163], v[188:191], v[92:95]
	v_mfma_f32_16x16x32_bf16 v[84:87], v[152:155], v[196:199], v[84:87]
	v_mfma_f32_16x16x32_bf16 v[76:79], v[160:163], v[196:199], v[76:79]
	s_setprio 0
	s_barrier
	s_add_i32 s12, s34, s25
	v_lshl_add_u64 v[168:169], s[16:17], 0, v[130:131]
	s_mov_b32 m0, s12
	ds_read_b128 v[200:203], v147
	ds_read_b128 v[204:207], v147 offset:1024
	ds_read_b128 v[208:211], v147 offset:2048
	ds_read_b128 v[212:215], v147 offset:3072
	global_load_lds_dwordx4 v[168:169], off
	v_lshl_add_u64 v[216:217], s[16:17], 0, v[128:129]
	s_add_i32 m0, s12, 0x2000
	s_nop 0
	global_load_lds_dwordx4 v[216:217], off
	s_barrier
	s_waitcnt lgkmcnt(0)
	s_setprio 1
	s_waitcnt lgkmcnt(0)
	v_mfma_f32_16x16x32_bf16 v[112:115], v[200:203], v[164:167], v[112:115]
	v_mfma_f32_16x16x32_bf16 v[104:107], v[208:211], v[164:167], v[104:107]
	v_mfma_f32_16x16x32_bf16 v[96:99], v[200:203], v[176:179], v[96:99]
	v_mfma_f32_16x16x32_bf16 v[88:91], v[208:211], v[176:179], v[88:91]
	v_mfma_f32_16x16x32_bf16 v[80:83], v[200:203], v[184:187], v[80:83]
	v_mfma_f32_16x16x32_bf16 v[72:75], v[208:211], v[184:187], v[72:75]
	v_mfma_f32_16x16x32_bf16 v[68:71], v[200:203], v[192:195], v[68:71]
	v_mfma_f32_16x16x32_bf16 v[64:67], v[208:211], v[192:195], v[64:67]
	v_mfma_f32_16x16x32_bf16 v[112:115], v[204:207], v[172:175], v[112:115]
	v_mfma_f32_16x16x32_bf16 v[104:107], v[212:215], v[172:175], v[104:107]
	v_mfma_f32_16x16x32_bf16 v[96:99], v[204:207], v[180:183], v[96:99]
	v_mfma_f32_16x16x32_bf16 v[88:91], v[212:215], v[180:183], v[88:91]
	v_mfma_f32_16x16x32_bf16 v[80:83], v[204:207], v[188:191], v[80:83]
	v_mfma_f32_16x16x32_bf16 v[72:75], v[212:215], v[188:191], v[72:75]
	v_mfma_f32_16x16x32_bf16 v[68:71], v[204:207], v[196:199], v[68:71]
	v_mfma_f32_16x16x32_bf16 v[64:67], v[212:215], v[196:199], v[64:67]
	s_setprio 0
	s_mov_b32 m0, s26
	v_lshl_add_u64 v[218:219], s[18:19], 0, v[130:131]
	s_barrier
	ds_read_b128 v[164:167], v146 offset:16384
	ds_read_b128 v[172:175], v146 offset:17408
	ds_read_b128 v[176:179], v146 offset:18432
	ds_read_b128 v[180:183], v146 offset:19456
	ds_read_b128 v[184:187], v146 offset:20480
	ds_read_b128 v[188:191], v146 offset:21504
	ds_read_b128 v[192:195], v146 offset:22528
	ds_read_b128 v[196:199], v146 offset:23552
	global_load_lds_dwordx4 v[218:219], off
	v_lshl_add_u64 v[220:221], s[18:19], 0, v[128:129]
	s_mov_b32 m0, s27
	s_nop 0
	global_load_lds_dwordx4 v[220:221], off
	s_barrier
	s_waitcnt lgkmcnt(0)
	s_setprio 1
	s_waitcnt lgkmcnt(0)
	v_mfma_f32_16x16x32_bf16 v[60:63], v[148:151], v[164:167], v[60:63]
	v_mfma_f32_16x16x32_bf16 v[56:59], v[156:159], v[164:167], v[56:59]
	v_mfma_f32_16x16x32_bf16 v[52:55], v[148:151], v[176:179], v[52:55]
	v_mfma_f32_16x16x32_bf16 v[44:47], v[156:159], v[176:179], v[44:47]
	v_mfma_f32_16x16x32_bf16 v[36:39], v[148:151], v[184:187], v[36:39]
	v_mfma_f32_16x16x32_bf16 v[28:31], v[156:159], v[184:187], v[28:31]
	v_mfma_f32_16x16x32_bf16 v[20:23], v[148:151], v[192:195], v[20:23]
	v_mfma_f32_16x16x32_bf16 v[12:15], v[156:159], v[192:195], v[12:15]
	v_mfma_f32_16x16x32_bf16 v[60:63], v[152:155], v[172:175], v[60:63]
	v_mfma_f32_16x16x32_bf16 v[56:59], v[160:163], v[172:175], v[56:59]
	v_mfma_f32_16x16x32_bf16 v[52:55], v[152:155], v[180:183], v[52:55]
	v_mfma_f32_16x16x32_bf16 v[44:47], v[160:163], v[180:183], v[44:47]
	v_mfma_f32_16x16x32_bf16 v[36:39], v[152:155], v[188:191], v[36:39]
	v_mfma_f32_16x16x32_bf16 v[28:31], v[160:163], v[188:191], v[28:31]
	v_mfma_f32_16x16x32_bf16 v[20:23], v[152:155], v[196:199], v[20:23]
	v_mfma_f32_16x16x32_bf16 v[12:15], v[160:163], v[196:199], v[12:15]
	s_setprio 0
	s_barrier
	s_add_u32 s12, s16, 0xb0000
	s_addc_u32 s13, s17, 0
	s_add_i32 s44, s35, s25
	v_lshl_add_u64 v[148:149], s[12:13], 0, v[130:131]
	s_mov_b32 m0, s44
	s_nop 0
	global_load_lds_dwordx4 v[148:149], off
	v_lshl_add_u64 v[148:149], s[12:13], 0, v[128:129]
	s_add_i32 m0, s44, 0x2000
	s_nop 0
	global_load_lds_dwordx4 v[148:149], off
	s_waitcnt vmcnt(6)
	s_barrier
	s_setprio 1
	v_mfma_f32_16x16x32_bf16 v[48:51], v[200:203], v[164:167], v[48:51]
	v_mfma_f32_16x16x32_bf16 v[40:43], v[208:211], v[164:167], v[40:43]
	v_mfma_f32_16x16x32_bf16 v[32:35], v[200:203], v[176:179], v[32:35]
	v_mfma_f32_16x16x32_bf16 v[24:27], v[208:211], v[176:179], v[24:27]
	v_mfma_f32_16x16x32_bf16 v[16:19], v[200:203], v[184:187], v[16:19]
	v_mfma_f32_16x16x32_bf16 v[8:11], v[208:211], v[184:187], v[8:11]
	v_mfma_f32_16x16x32_bf16 v[4:7], v[200:203], v[192:195], v[4:7]
	v_mfma_f32_16x16x32_bf16 v[0:3], v[208:211], v[192:195], v[0:3]
	v_mfma_f32_16x16x32_bf16 v[48:51], v[204:207], v[172:175], v[48:51]
	v_mfma_f32_16x16x32_bf16 v[40:43], v[212:215], v[172:175], v[40:43]
	v_mfma_f32_16x16x32_bf16 v[32:35], v[204:207], v[180:183], v[32:35]
	v_mfma_f32_16x16x32_bf16 v[24:27], v[212:215], v[180:183], v[24:27]
	v_mfma_f32_16x16x32_bf16 v[16:19], v[204:207], v[188:191], v[16:19]
	v_mfma_f32_16x16x32_bf16 v[8:11], v[212:215], v[188:191], v[8:11]
	v_mfma_f32_16x16x32_bf16 v[4:7], v[204:207], v[196:199], v[4:7]
	v_mfma_f32_16x16x32_bf16 v[0:3], v[212:215], v[196:199], v[0:3]
	s_setprio 0
	s_add_i32 s44, 0, 0x18000
	v_add_u32_e32 v160, s44, v144
	s_barrier
	ds_read_b128 v[148:151], v160
	ds_read_b128 v[152:155], v160 offset:1024
	ds_read_b128 v[156:159], v160 offset:2048
	ds_read_b128 v[160:163], v160 offset:3072
	s_add_u32 s12, s18, 0xb0000
	s_addc_u32 s13, s19, 0
	s_mov_b32 m0, s28
	v_lshl_add_u64 v[200:201], s[12:13], 0, v[130:131]
	ds_read_b128 v[164:167], v146 offset:32768
	ds_read_b128 v[172:175], v146 offset:33792
	ds_read_b128 v[176:179], v146 offset:34816
	ds_read_b128 v[180:183], v146 offset:35840
	ds_read_b128 v[184:187], v146 offset:36864
	ds_read_b128 v[188:191], v146 offset:37888
	ds_read_b128 v[192:195], v146 offset:38912
	ds_read_b128 v[196:199], v146 offset:39936
	global_load_lds_dwordx4 v[200:201], off
	v_lshl_add_u64 v[200:201], s[12:13], 0, v[128:129]
	s_mov_b32 m0, s29
	s_nop 0
	global_load_lds_dwordx4 v[200:201], off
	s_waitcnt lgkmcnt(8)
	s_barrier
	s_waitcnt lgkmcnt(0)
	s_setprio 1
	s_waitcnt lgkmcnt(0)
	v_mfma_f32_16x16x32_bf16 v[124:127], v[148:151], v[164:167], v[124:127]
	v_mfma_f32_16x16x32_bf16 v[120:123], v[156:159], v[164:167], v[120:123]
	v_mfma_f32_16x16x32_bf16 v[116:119], v[148:151], v[176:179], v[116:119]
	v_mfma_f32_16x16x32_bf16 v[108:111], v[156:159], v[176:179], v[108:111]
	v_mfma_f32_16x16x32_bf16 v[100:103], v[148:151], v[184:187], v[100:103]
	v_mfma_f32_16x16x32_bf16 v[92:95], v[156:159], v[184:187], v[92:95]
	v_mfma_f32_16x16x32_bf16 v[84:87], v[148:151], v[192:195], v[84:87]
	v_mfma_f32_16x16x32_bf16 v[76:79], v[156:159], v[192:195], v[76:79]
	v_mfma_f32_16x16x32_bf16 v[124:127], v[152:155], v[172:175], v[124:127]
	v_mfma_f32_16x16x32_bf16 v[120:123], v[160:163], v[172:175], v[120:123]
	v_mfma_f32_16x16x32_bf16 v[116:119], v[152:155], v[180:183], v[116:119]
	v_mfma_f32_16x16x32_bf16 v[108:111], v[160:163], v[180:183], v[108:111]
	v_mfma_f32_16x16x32_bf16 v[100:103], v[152:155], v[188:191], v[100:103]
	v_mfma_f32_16x16x32_bf16 v[92:95], v[160:163], v[188:191], v[92:95]
	v_mfma_f32_16x16x32_bf16 v[84:87], v[152:155], v[196:199], v[84:87]
	v_mfma_f32_16x16x32_bf16 v[76:79], v[160:163], v[196:199], v[76:79]
	s_setprio 0
	s_barrier
	s_add_i32 s18, 0, 0x1c000
	s_add_i32 s12, s44, s25
	v_add_u32_e32 v171, s18, v144
	v_lshl_add_u64 v[168:169], v[168:169], 0, s[10:11]
	s_mov_b32 m0, s12
	ds_read_b128 v[200:203], v171
	ds_read_b128 v[204:207], v171 offset:1024
	ds_read_b128 v[208:211], v171 offset:2048
	ds_read_b128 v[212:215], v171 offset:3072
	global_load_lds_dwordx4 v[168:169], off
	v_lshl_add_u64 v[168:169], v[216:217], 0, s[10:11]
	s_add_i32 m0, s12, 0x2000
	s_nop 0
	global_load_lds_dwordx4 v[168:169], off
	s_barrier
	s_waitcnt lgkmcnt(0)
	s_setprio 1
	s_waitcnt lgkmcnt(0)
	v_mfma_f32_16x16x32_bf16 v[112:115], v[200:203], v[164:167], v[112:115]
	v_mfma_f32_16x16x32_bf16 v[104:107], v[208:211], v[164:167], v[104:107]
	v_mfma_f32_16x16x32_bf16 v[96:99], v[200:203], v[176:179], v[96:99]
	v_mfma_f32_16x16x32_bf16 v[88:91], v[208:211], v[176:179], v[88:91]
	v_mfma_f32_16x16x32_bf16 v[80:83], v[200:203], v[184:187], v[80:83]
	v_mfma_f32_16x16x32_bf16 v[72:75], v[208:211], v[184:187], v[72:75]
	v_mfma_f32_16x16x32_bf16 v[68:71], v[200:203], v[192:195], v[68:71]
	v_mfma_f32_16x16x32_bf16 v[64:67], v[208:211], v[192:195], v[64:67]
	v_mfma_f32_16x16x32_bf16 v[112:115], v[204:207], v[172:175], v[112:115]
	v_mfma_f32_16x16x32_bf16 v[104:107], v[212:215], v[172:175], v[104:107]
	v_mfma_f32_16x16x32_bf16 v[96:99], v[204:207], v[180:183], v[96:99]
	v_mfma_f32_16x16x32_bf16 v[88:91], v[212:215], v[180:183], v[88:91]
	v_mfma_f32_16x16x32_bf16 v[80:83], v[204:207], v[188:191], v[80:83]
	v_mfma_f32_16x16x32_bf16 v[72:75], v[212:215], v[188:191], v[72:75]
	v_mfma_f32_16x16x32_bf16 v[68:71], v[204:207], v[196:199], v[68:71]
	v_mfma_f32_16x16x32_bf16 v[64:67], v[212:215], v[196:199], v[64:67]
	s_setprio 0
	s_mov_b32 m0, s30
	v_lshl_add_u64 v[168:169], v[218:219], 0, s[10:11]
	s_barrier
	ds_read_b128 v[164:167], v146 offset:49152
	ds_read_b128 v[172:175], v146 offset:50176
	ds_read_b128 v[176:179], v146 offset:51200
	ds_read_b128 v[180:183], v146 offset:52224
	ds_read_b128 v[184:187], v146 offset:53248
	ds_read_b128 v[188:191], v146 offset:54272
	ds_read_b128 v[192:195], v146 offset:55296
	ds_read_b128 v[196:199], v146 offset:56320
	global_load_lds_dwordx4 v[168:169], off
	v_lshl_add_u64 v[168:169], v[220:221], 0, s[10:11]
	s_mov_b32 m0, s31
	s_nop 0
	global_load_lds_dwordx4 v[168:169], off
	s_barrier
	s_waitcnt lgkmcnt(0)
	s_setprio 1
	s_waitcnt lgkmcnt(0)
	v_mfma_f32_16x16x32_bf16 v[60:63], v[148:151], v[164:167], v[60:63]
	v_mfma_f32_16x16x32_bf16 v[56:59], v[156:159], v[164:167], v[56:59]
	v_mfma_f32_16x16x32_bf16 v[52:55], v[148:151], v[176:179], v[52:55]
	v_mfma_f32_16x16x32_bf16 v[44:47], v[156:159], v[176:179], v[44:47]
	v_mfma_f32_16x16x32_bf16 v[36:39], v[148:151], v[184:187], v[36:39]
	v_mfma_f32_16x16x32_bf16 v[28:31], v[156:159], v[184:187], v[28:31]
	v_mfma_f32_16x16x32_bf16 v[20:23], v[148:151], v[192:195], v[20:23]
	v_mfma_f32_16x16x32_bf16 v[12:15], v[156:159], v[192:195], v[12:15]
	v_mfma_f32_16x16x32_bf16 v[60:63], v[152:155], v[172:175], v[60:63]
	v_mfma_f32_16x16x32_bf16 v[56:59], v[160:163], v[172:175], v[56:59]
	v_mfma_f32_16x16x32_bf16 v[52:55], v[152:155], v[180:183], v[52:55]
	v_mfma_f32_16x16x32_bf16 v[44:47], v[160:163], v[180:183], v[44:47]
	v_mfma_f32_16x16x32_bf16 v[36:39], v[152:155], v[188:191], v[36:39]
	v_mfma_f32_16x16x32_bf16 v[28:31], v[160:163], v[188:191], v[28:31]
	v_mfma_f32_16x16x32_bf16 v[20:23], v[152:155], v[196:199], v[20:23]
	v_mfma_f32_16x16x32_bf16 v[12:15], v[160:163], v[196:199], v[12:15]
	s_setprio 0
	s_barrier
	s_add_u32 s12, s16, 0xb0080
	s_addc_u32 s13, s17, 0
	s_add_i32 s16, s18, s25
	v_lshl_add_u64 v[148:149], s[12:13], 0, v[130:131]
	s_mov_b32 m0, s16
	s_nop 0
	global_load_lds_dwordx4 v[148:149], off
	v_lshl_add_u64 v[148:149], s[12:13], 0, v[128:129]
	s_add_i32 m0, s16, 0x2000
	s_nop 0
	global_load_lds_dwordx4 v[148:149], off
	s_waitcnt vmcnt(6)
	s_barrier
	s_setprio 1
	v_mfma_f32_16x16x32_bf16 v[48:51], v[200:203], v[164:167], v[48:51]
	v_mfma_f32_16x16x32_bf16 v[40:43], v[208:211], v[164:167], v[40:43]
	v_mfma_f32_16x16x32_bf16 v[32:35], v[200:203], v[176:179], v[32:35]
	v_mfma_f32_16x16x32_bf16 v[24:27], v[208:211], v[176:179], v[24:27]
	v_mfma_f32_16x16x32_bf16 v[16:19], v[200:203], v[184:187], v[16:19]
	v_mfma_f32_16x16x32_bf16 v[8:11], v[208:211], v[184:187], v[8:11]
	v_mfma_f32_16x16x32_bf16 v[4:7], v[200:203], v[192:195], v[4:7]
	v_mfma_f32_16x16x32_bf16 v[0:3], v[208:211], v[192:195], v[0:3]
	v_mfma_f32_16x16x32_bf16 v[48:51], v[204:207], v[172:175], v[48:51]
	v_mfma_f32_16x16x32_bf16 v[40:43], v[212:215], v[172:175], v[40:43]
	v_mfma_f32_16x16x32_bf16 v[32:35], v[204:207], v[180:183], v[32:35]
	v_mfma_f32_16x16x32_bf16 v[24:27], v[212:215], v[180:183], v[24:27]
	v_mfma_f32_16x16x32_bf16 v[16:19], v[204:207], v[188:191], v[16:19]
	v_mfma_f32_16x16x32_bf16 v[8:11], v[212:215], v[188:191], v[8:11]
	v_mfma_f32_16x16x32_bf16 v[4:7], v[204:207], v[196:199], v[4:7]
	v_mfma_f32_16x16x32_bf16 v[0:3], v[212:215], v[196:199], v[0:3]
	s_setprio 0
	s_add_i32 s43, s43, 2
	s_add_u32 s41, s41, 0x100
	s_addc_u32 s42, s42, 0
	s_cmp_gt_u32 s43, 41
	s_mov_b64 s[12:13], s[14:15]
	s_barrier
	s_cbranch_scc0 .LBB0_2279
	v_readlane_b32 s12, v235, 24
	v_lshl_add_u32 v148, s12, 8, v143
	v_readlane_b32 s12, v235, 16
	s_lshl_b32 s12, s12, 8
	v_ashrrev_i32_e32 v149, 31, v148
	s_ashr_i32 s13, s12, 31
	v_lshlrev_b64 v[150:151], 11, v[148:149]
	v_lshl_add_u64 v[150:151], s[2:3], 0, v[150:151]
	s_lshl_b64 s[12:13], s[12:13], 1
	v_lshl_add_u64 v[150:151], v[150:151], 0, s[12:13]
	v_lshl_add_u64 v[150:151], v[150:151], 0, s[8:9]
	v_lshl_add_u64 v[150:151], v[150:151], 0, v[132:133]
	v_mbcnt_lo_u32_b32 v237, -1, 0
	v_mbcnt_hi_u32_b32 v237, -1, v237
	v_bfe_i32 v237, v237, 4, 1
	v_and_b32_e32 v244, 24, v237
	v_add_co_u32_e32 v248, vcc, v244, v150
	s_nop 1
	v_addc_co_u32_e32 v249, vcc, 0, v151, vcc
	v_cvt_pk_bf16_f32 v124, v124, v125
	v_cvt_pk_bf16_f32 v125, v126, v127
	v_cvt_pk_bf16_f32 v120, v120, v121
	v_cvt_pk_bf16_f32 v121, v122, v123
	v_bfi_b32 v244, v237, v124, v120
	v_bfi_b32 v245, v237, v125, v121
	ds_swizzle_b32 v250, v244 offset:0x401f
	ds_swizzle_b32 v251, v245 offset:0x401f
	v_cvt_pk_bf16_f32 v112, v112, v113
	v_cvt_pk_bf16_f32 v113, v114, v115
	v_cvt_pk_bf16_f32 v104, v104, v105
	v_cvt_pk_bf16_f32 v105, v106, v107
	v_bfi_b32 v246, v237, v112, v104
	v_bfi_b32 v247, v237, v113, v105
	ds_swizzle_b32 v252, v246 offset:0x401f
	ds_swizzle_b32 v253, v247 offset:0x401f
	s_waitcnt lgkmcnt(0)
	v_bfi_b32 v240, v237, v250, v124
	v_bfi_b32 v241, v237, v251, v125
	v_bfi_b32 v242, v237, v120, v250
	v_bfi_b32 v243, v237, v121, v251
	global_store_dwordx4 v[248:249], v[240:243], off
	s_nop 1
	v_bfi_b32 v240, v237, v252, v112
	v_bfi_b32 v241, v237, v253, v113
	v_bfi_b32 v242, v237, v104, v252
	v_bfi_b32 v243, v237, v105, v253
	global_store_dwordx4 v[248:249], v[240:243], off offset:256
	s_nop 1
	v_add_co_u32_e32 v238, vcc, 0x8000, v248
	s_nop 1
	v_addc_co_u32_e32 v239, vcc, 0, v249, vcc
	v_cvt_pk_bf16_f32 v116, v116, v117
	v_cvt_pk_bf16_f32 v117, v118, v119
	v_cvt_pk_bf16_f32 v108, v108, v109
	v_cvt_pk_bf16_f32 v109, v110, v111
	v_bfi_b32 v244, v237, v116, v108
	v_bfi_b32 v245, v237, v117, v109
	ds_swizzle_b32 v250, v244 offset:0x401f
	ds_swizzle_b32 v251, v245 offset:0x401f
	v_cvt_pk_bf16_f32 v96, v96, v97
	v_cvt_pk_bf16_f32 v97, v98, v99
	v_cvt_pk_bf16_f32 v88, v88, v89
	v_cvt_pk_bf16_f32 v89, v90, v91
	v_bfi_b32 v246, v237, v96, v88
	v_bfi_b32 v247, v237, v97, v89
	ds_swizzle_b32 v252, v246 offset:0x401f
	ds_swizzle_b32 v253, v247 offset:0x401f
	s_waitcnt lgkmcnt(0)
	v_bfi_b32 v240, v237, v250, v116
	v_bfi_b32 v241, v237, v251, v117
	v_bfi_b32 v242, v237, v108, v250
	v_bfi_b32 v243, v237, v109, v251
	global_store_dwordx4 v[238:239], v[240:243], off
	s_nop 1
	v_bfi_b32 v240, v237, v252, v96
	v_bfi_b32 v241, v237, v253, v97
	v_bfi_b32 v242, v237, v88, v252
	v_bfi_b32 v243, v237, v89, v253
	global_store_dwordx4 v[238:239], v[240:243], off offset:256
	s_nop 1
	v_add_co_u32_e32 v238, vcc, 0x10000, v248
	s_nop 1
	v_addc_co_u32_e32 v239, vcc, 0, v249, vcc
	v_cvt_pk_bf16_f32 v100, v100, v101
	v_cvt_pk_bf16_f32 v101, v102, v103
	v_cvt_pk_bf16_f32 v92, v92, v93
	v_cvt_pk_bf16_f32 v93, v94, v95
	v_bfi_b32 v244, v237, v100, v92
	v_bfi_b32 v245, v237, v101, v93
	ds_swizzle_b32 v250, v244 offset:0x401f
	ds_swizzle_b32 v251, v245 offset:0x401f
	v_cvt_pk_bf16_f32 v80, v80, v81
	v_cvt_pk_bf16_f32 v81, v82, v83
	v_cvt_pk_bf16_f32 v72, v72, v73
	v_cvt_pk_bf16_f32 v73, v74, v75
	v_bfi_b32 v246, v237, v80, v72
	v_bfi_b32 v247, v237, v81, v73
	ds_swizzle_b32 v252, v246 offset:0x401f
	ds_swizzle_b32 v253, v247 offset:0x401f
	s_waitcnt lgkmcnt(0)
	v_bfi_b32 v240, v237, v250, v100
	v_bfi_b32 v241, v237, v251, v101
	v_bfi_b32 v242, v237, v92, v250
	v_bfi_b32 v243, v237, v93, v251
	global_store_dwordx4 v[238:239], v[240:243], off
	s_nop 1
	v_bfi_b32 v240, v237, v252, v80
	v_bfi_b32 v241, v237, v253, v81
	v_bfi_b32 v242, v237, v72, v252
	v_bfi_b32 v243, v237, v73, v253
	global_store_dwordx4 v[238:239], v[240:243], off offset:256
	s_nop 1
	v_add_co_u32_e32 v238, vcc, 0x18000, v248
	s_nop 1
	v_addc_co_u32_e32 v239, vcc, 0, v249, vcc
	v_cvt_pk_bf16_f32 v84, v84, v85
	v_cvt_pk_bf16_f32 v85, v86, v87
	v_cvt_pk_bf16_f32 v76, v76, v77
	v_cvt_pk_bf16_f32 v77, v78, v79
	v_bfi_b32 v244, v237, v84, v76
	v_bfi_b32 v245, v237, v85, v77
	ds_swizzle_b32 v250, v244 offset:0x401f
	ds_swizzle_b32 v251, v245 offset:0x401f
	v_cvt_pk_bf16_f32 v68, v68, v69
	v_cvt_pk_bf16_f32 v69, v70, v71
	v_cvt_pk_bf16_f32 v64, v64, v65
	v_cvt_pk_bf16_f32 v65, v66, v67
	v_bfi_b32 v246, v237, v68, v64
	v_bfi_b32 v247, v237, v69, v65
	ds_swizzle_b32 v252, v246 offset:0x401f
	ds_swizzle_b32 v253, v247 offset:0x401f
	s_waitcnt lgkmcnt(0)
	v_bfi_b32 v240, v237, v250, v84
	v_bfi_b32 v241, v237, v251, v85
	v_bfi_b32 v242, v237, v76, v250
	v_bfi_b32 v243, v237, v77, v251
	global_store_dwordx4 v[238:239], v[240:243], off
	s_nop 1
	v_bfi_b32 v240, v237, v252, v68
	v_bfi_b32 v241, v237, v253, v69
	v_bfi_b32 v242, v237, v64, v252
	v_bfi_b32 v243, v237, v65, v253
	global_store_dwordx4 v[238:239], v[240:243], off offset:256
	s_nop 1
	v_add_co_u32_e32 v238, vcc, 0x40000, v248
	s_nop 1
	v_addc_co_u32_e32 v239, vcc, 0, v249, vcc
	v_cvt_pk_bf16_f32 v60, v60, v61
	v_cvt_pk_bf16_f32 v61, v62, v63
	v_cvt_pk_bf16_f32 v56, v56, v57
	v_cvt_pk_bf16_f32 v57, v58, v59
	v_bfi_b32 v244, v237, v60, v56
	v_bfi_b32 v245, v237, v61, v57
	ds_swizzle_b32 v250, v244 offset:0x401f
	ds_swizzle_b32 v251, v245 offset:0x401f
	v_cvt_pk_bf16_f32 v48, v48, v49
	v_cvt_pk_bf16_f32 v49, v50, v51
	v_cvt_pk_bf16_f32 v40, v40, v41
	v_cvt_pk_bf16_f32 v41, v42, v43
	v_bfi_b32 v246, v237, v48, v40
	v_bfi_b32 v247, v237, v49, v41
	ds_swizzle_b32 v252, v246 offset:0x401f
	ds_swizzle_b32 v253, v247 offset:0x401f
	s_waitcnt lgkmcnt(0)
	v_bfi_b32 v240, v237, v250, v60
	v_bfi_b32 v241, v237, v251, v61
	v_bfi_b32 v242, v237, v56, v250
	v_bfi_b32 v243, v237, v57, v251
	global_store_dwordx4 v[238:239], v[240:243], off
	s_nop 1
	v_bfi_b32 v240, v237, v252, v48
	v_bfi_b32 v241, v237, v253, v49
	v_bfi_b32 v242, v237, v40, v252
	v_bfi_b32 v243, v237, v41, v253
	global_store_dwordx4 v[238:239], v[240:243], off offset:256
	s_nop 1
	v_add_co_u32_e32 v238, vcc, 0x48000, v248
	s_nop 1
	v_addc_co_u32_e32 v239, vcc, 0, v249, vcc
	v_cvt_pk_bf16_f32 v52, v52, v53
	v_cvt_pk_bf16_f32 v53, v54, v55
	v_cvt_pk_bf16_f32 v44, v44, v45
	v_cvt_pk_bf16_f32 v45, v46, v47
	v_bfi_b32 v244, v237, v52, v44
	v_bfi_b32 v245, v237, v53, v45
	ds_swizzle_b32 v250, v244 offset:0x401f
	ds_swizzle_b32 v251, v245 offset:0x401f
	v_cvt_pk_bf16_f32 v32, v32, v33
	v_cvt_pk_bf16_f32 v33, v34, v35
	v_cvt_pk_bf16_f32 v24, v24, v25
	v_cvt_pk_bf16_f32 v25, v26, v27
	v_bfi_b32 v246, v237, v32, v24
	v_bfi_b32 v247, v237, v33, v25
	ds_swizzle_b32 v252, v246 offset:0x401f
	ds_swizzle_b32 v253, v247 offset:0x401f
	s_waitcnt lgkmcnt(0)
	v_bfi_b32 v240, v237, v250, v52
	v_bfi_b32 v241, v237, v251, v53
	v_bfi_b32 v242, v237, v44, v250
	v_bfi_b32 v243, v237, v45, v251
	global_store_dwordx4 v[238:239], v[240:243], off
	s_nop 1
	v_bfi_b32 v240, v237, v252, v32
	v_bfi_b32 v241, v237, v253, v33
	v_bfi_b32 v242, v237, v24, v252
	v_bfi_b32 v243, v237, v25, v253
	global_store_dwordx4 v[238:239], v[240:243], off offset:256
	s_nop 1
	v_add_co_u32_e32 v238, vcc, 0x50000, v248
	s_nop 1
	v_addc_co_u32_e32 v239, vcc, 0, v249, vcc
	v_cvt_pk_bf16_f32 v36, v36, v37
	v_cvt_pk_bf16_f32 v37, v38, v39
	v_cvt_pk_bf16_f32 v28, v28, v29
	v_cvt_pk_bf16_f32 v29, v30, v31
	v_bfi_b32 v244, v237, v36, v28
	v_bfi_b32 v245, v237, v37, v29
	ds_swizzle_b32 v250, v244 offset:0x401f
	ds_swizzle_b32 v251, v245 offset:0x401f
	v_cvt_pk_bf16_f32 v16, v16, v17
	v_cvt_pk_bf16_f32 v17, v18, v19
	v_cvt_pk_bf16_f32 v8, v8, v9
	v_cvt_pk_bf16_f32 v9, v10, v11
	v_bfi_b32 v246, v237, v16, v8
	v_bfi_b32 v247, v237, v17, v9
	ds_swizzle_b32 v252, v246 offset:0x401f
	ds_swizzle_b32 v253, v247 offset:0x401f
	s_waitcnt lgkmcnt(0)
	v_bfi_b32 v240, v237, v250, v36
	v_bfi_b32 v241, v237, v251, v37
	v_bfi_b32 v242, v237, v28, v250
	v_bfi_b32 v243, v237, v29, v251
	global_store_dwordx4 v[238:239], v[240:243], off
	s_nop 1
	v_bfi_b32 v240, v237, v252, v16
	v_bfi_b32 v241, v237, v253, v17
	v_bfi_b32 v242, v237, v8, v252
	v_bfi_b32 v243, v237, v9, v253
	global_store_dwordx4 v[238:239], v[240:243], off offset:256
	s_nop 1
	v_add_co_u32_e32 v238, vcc, 0x58000, v248
	s_nop 1
	v_addc_co_u32_e32 v239, vcc, 0, v249, vcc
	v_cvt_pk_bf16_f32 v20, v20, v21
	v_cvt_pk_bf16_f32 v21, v22, v23
	v_cvt_pk_bf16_f32 v12, v12, v13
	v_cvt_pk_bf16_f32 v13, v14, v15
	v_bfi_b32 v244, v237, v20, v12
	v_bfi_b32 v245, v237, v21, v13
	ds_swizzle_b32 v250, v244 offset:0x401f
	ds_swizzle_b32 v251, v245 offset:0x401f
	v_cvt_pk_bf16_f32 v4, v4, v5
	v_cvt_pk_bf16_f32 v5, v6, v7
	v_cvt_pk_bf16_f32 v0, v0, v1
	v_cvt_pk_bf16_f32 v1, v2, v3
	v_bfi_b32 v246, v237, v4, v0
	v_bfi_b32 v247, v237, v5, v1
	ds_swizzle_b32 v252, v246 offset:0x401f
	ds_swizzle_b32 v253, v247 offset:0x401f
	s_waitcnt lgkmcnt(0)
	v_bfi_b32 v240, v237, v250, v20
	v_bfi_b32 v241, v237, v251, v21
	v_bfi_b32 v242, v237, v12, v250
	v_bfi_b32 v243, v237, v13, v251
	global_store_dwordx4 v[238:239], v[240:243], off
	s_nop 1
	v_bfi_b32 v240, v237, v252, v4
	v_bfi_b32 v241, v237, v253, v5
	v_bfi_b32 v242, v237, v0, v252
	v_bfi_b32 v243, v237, v1, v253
	global_store_dwordx4 v[238:239], v[240:243], off offset:256
	s_nop 1
	s_and_b64 vcc, exec, s[4:5]
	v_writelane_b32 v235, s39, 16
	s_mov_b64 s[14:15], s[0:1]
	s_mov_b64 s[12:13], s[6:7]
	v_writelane_b32 v235, s40, 24
	s_cbranch_vccz .LBB0_2272
	s_waitcnt vmcnt(0)
	s_cmpk_gt_u32 s20, 0xff
	s_cbranch_scc1 .LBB0_2283
	s_barrier
